# v10c: MFMA order m,(4 n of both groups),k-inner (second operand reused over 8)
# baseline (speedup 1.0000x reference)
; #define PG8_STAGE(bufoff, gbase, voff) do { _Pragma("unroll") for (int _i = 0; _i < 2; ++_i) \
;         __builtin_amdgcn_global_load_lds((const unsigned*)((const char*)(gbase) + (voff)[_i]), (PG8_LAS unsigned*)(lds + (bufoff) + ldsw + _i * 8192), 16, 0, 0); } while (0)
; #define PG8_LDA(dst, b, h) do { _Pragma("unroll") for (int m = 0; m < 4; ++m) _Pragma("unroll") for (int k = 0; k < 2; ++k) dst[m][k] = *(const PG8_LAS bf16x8*)(lds + PG8_SA(b, h) + aoff + m * 2048 + k * 1024); } while (0)
; #define PG8_LDB(dst, b, h) do { _Pragma("unroll") for (int n = 0; n < 2; ++n) _Pragma("unroll") for (int k = 0; k < 2; ++k) dst[n][k] = *(const PG8_LAS bf16x8*)(lds + PG8_SB(b, h) + boff + n * 2048 + k * 1024); } while (0)
; #define PG8_MMA(ai, bj, At, Bt) do { __builtin_amdgcn_s_setprio(1); _Pragma("unroll") for (int m = 0; m < 4; ++m) _Pragma("unroll") for (int n = 0; n < 2; ++n) _Pragma("unroll") for (int k = 0; k < 2; ++k) \
;         acc[ai][bj][m][n] = __builtin_amdgcn_mfma_f32_16x16x32_bf16(Bt[n][k], At[m][k], acc[ai][bj][m][n], 0, 0, 0); __builtin_amdgcn_s_setprio(0); } while (0)
; #define PG8_WAIT_V(n) asm volatile("s_waitcnt vmcnt(" #n ")" ::: "memory")
; #define PG8_WAIT_L(n) asm volatile("s_waitcnt lgkmcnt(" #n ")" ::: "memory")
; template <class Epi, class Sched, bool ALIGN_EPI = false, bool SP2 = false>
; __device__ __forceinline__ void gemm_phase(PG8_LAS unsigned char* lds, const Gemm g, const Sched& S, const Epi& E) {
;     ...
;         for (; t < tend; t += 2) {
;             const bool last = (t == nt - 2);
;             const char* a1 = cA + (size_t)(t + 1) * kstep;
;             const char* a2 = last ? nA : cA + (size_t)(t + 2) * kstep; const char* b2 = last ? nB : cB + (size_t)(t + 2) * kstep;
;             const char* a3 = a2 + kstep; const char* b3 = b2 + kstep;
;             if (last && has_next) S.a_ready(nxt);
;             if constexpr (SP2) {
;             PG8_LDB(B0, 0, 0); PG8_LDB(B1, 0, 1); PG8_SCHED; PG8_LDA(At, 0, 0); PG8_STAGE(PG8_SA(1, 1), a1 + hstep, voffA);
;             PG8_WAIT_V(8); PG8_WAIT_L(0); PG8_BAR; PG8_MMA(0, 0, At, B0); PG8_MMA(0, 1, At, B1); PG8_BAR; PG8_SCHED;
;             PG8_LDA(At, 0, 1); PG8_STAGE(PG8_SB(0, 0), b2, voffB); PG8_STAGE(PG8_SB(0, 1), b2 + hstep, voffB); PG8_STAGE(PG8_SA(0, 0), a2, voffA);
;             PG8_WAIT_V(8); PG8_WAIT_L(0); PG8_BAR; PG8_MMA(1, 0, At, B0); PG8_MMA(1, 1, At, B1); PG8_BAR; PG8_SCHED;
.LBB0_115:
	ds_read_b128 v[154:157], v150
	ds_read_b128 v[158:161], v150 offset:1024
	ds_read_b128 v[162:165], v150 offset:2048
	ds_read_b128 v[166:169], v150 offset:3072
	ds_read_b128 v[170:173], v151
	ds_read_b128 v[174:177], v151 offset:1024
	ds_read_b128 v[180:183], v151 offset:2048
	ds_read_b128 v[184:187], v151 offset:3072
	s_add_u32 s50, s48, 0x4000
	s_addc_u32 s51, s49, 0
	s_cmp_eq_u32 s76, 60
	s_cselect_b32 s74, s64, s50
	s_cselect_b32 s75, s25, s51
	s_cselect_b32 s72, s65, s68
	s_cselect_b32 s73, s19, s69
	s_add_u32 s50, s74, 0x8000
	s_addc_u32 s51, s75, 0
	s_sub_u32 s50, s48, 0x4000
	s_subb_u32 s51, s49, 0
	v_lshl_add_u64 v[224:225], s[50:51], 0, v[130:131]
	s_mov_b32 m0, s58
	s_nop 0
	global_load_lds_dwordx4 v[224:225], off
	v_lshl_add_u64 v[224:225], s[50:51], 0, v[134:135]
	s_mov_b32 m0, s59
	s_nop 0
	global_load_lds_dwordx4 v[224:225], off
	v_lshl_add_u64 v[224:225], s[48:49], 0, v[140:141]
	s_add_i32 m0, s28, 0xc000
	ds_read_b128 v[188:191], v152
	ds_read_b128 v[196:199], v152 offset:1024
	ds_read_b128 v[200:203], v152 offset:2048
	ds_read_b128 v[204:207], v152 offset:3072
	ds_read_b128 v[208:211], v152 offset:4096
	ds_read_b128 v[212:215], v152 offset:5120
	ds_read_b128 v[216:219], v152 offset:6144
	ds_read_b128 v[220:223], v152 offset:7168
	global_load_lds_dwordx4 v[224:225], off
	v_lshl_add_u64 v[224:225], s[48:49], 0, v[142:143]
	s_add_i32 m0, s28, 0xe000
	s_nop 0
	global_load_lds_dwordx4 v[224:225], off
	s_waitcnt vmcnt(8)
	s_waitcnt lgkmcnt(0)
	s_barrier
	s_setprio 1
	s_waitcnt lgkmcnt(0)
	v_mfma_f32_16x16x32_bf16 v[126:129], v[154:157], v[188:191], v[126:129]
	v_mfma_f32_16x16x32_bf16 v[126:129], v[158:161], v[196:199], v[126:129]
	v_mfma_f32_16x16x32_bf16 v[118:121], v[162:165], v[188:191], v[118:121]
	v_mfma_f32_16x16x32_bf16 v[118:121], v[166:169], v[196:199], v[118:121]
	v_mfma_f32_16x16x32_bf16 v[122:125], v[170:173], v[188:191], v[122:125]
	v_mfma_f32_16x16x32_bf16 v[122:125], v[174:177], v[196:199], v[122:125]
	v_mfma_f32_16x16x32_bf16 v[114:117], v[180:183], v[188:191], v[114:117]
	v_mfma_f32_16x16x32_bf16 v[114:117], v[184:187], v[196:199], v[114:117]
	v_mfma_f32_16x16x32_bf16 v[110:113], v[154:157], v[200:203], v[110:113]
	v_mfma_f32_16x16x32_bf16 v[110:113], v[158:161], v[204:207], v[110:113]
	v_mfma_f32_16x16x32_bf16 v[102:105], v[162:165], v[200:203], v[102:105]
	v_mfma_f32_16x16x32_bf16 v[102:105], v[166:169], v[204:207], v[102:105]
	v_mfma_f32_16x16x32_bf16 v[106:109], v[170:173], v[200:203], v[106:109]
	v_mfma_f32_16x16x32_bf16 v[106:109], v[174:177], v[204:207], v[106:109]
	v_mfma_f32_16x16x32_bf16 v[98:101], v[180:183], v[200:203], v[98:101]
	v_mfma_f32_16x16x32_bf16 v[98:101], v[184:187], v[204:207], v[98:101]
	s_setprio 0
	s_setprio 1
	v_mfma_f32_16x16x32_bf16 v[94:97], v[154:157], v[208:211], v[94:97]
	v_mfma_f32_16x16x32_bf16 v[94:97], v[158:161], v[212:215], v[94:97]
	v_mfma_f32_16x16x32_bf16 v[86:89], v[162:165], v[208:211], v[86:89]
	v_mfma_f32_16x16x32_bf16 v[86:89], v[166:169], v[212:215], v[86:89]
	v_mfma_f32_16x16x32_bf16 v[90:93], v[170:173], v[208:211], v[90:93]
	v_mfma_f32_16x16x32_bf16 v[90:93], v[174:177], v[212:215], v[90:93]
	v_mfma_f32_16x16x32_bf16 v[82:85], v[180:183], v[208:211], v[82:85]
	v_mfma_f32_16x16x32_bf16 v[82:85], v[184:187], v[212:215], v[82:85]
	v_mfma_f32_16x16x32_bf16 v[78:81], v[154:157], v[216:219], v[78:81]
	v_mfma_f32_16x16x32_bf16 v[78:81], v[158:161], v[220:223], v[78:81]
	v_mfma_f32_16x16x32_bf16 v[70:73], v[162:165], v[216:219], v[70:73]
	v_mfma_f32_16x16x32_bf16 v[70:73], v[166:169], v[220:223], v[70:73]
	v_mfma_f32_16x16x32_bf16 v[74:77], v[170:173], v[216:219], v[74:77]
	v_mfma_f32_16x16x32_bf16 v[74:77], v[174:177], v[220:223], v[74:77]
	v_mfma_f32_16x16x32_bf16 v[66:69], v[180:183], v[216:219], v[66:69]
	v_mfma_f32_16x16x32_bf16 v[66:69], v[184:187], v[220:223], v[66:69]
	s_setprio 0
	s_barrier
	s_add_i32 s77, s61, s3
	v_lshl_add_u64 v[224:225], s[72:73], 0, v[132:133]
	s_mov_b32 m0, s77
	ds_read_b128 v[188:191], v152 offset:16384
	ds_read_b128 v[196:199], v152 offset:17408
	ds_read_b128 v[200:203], v152 offset:18432
	ds_read_b128 v[204:207], v152 offset:19456
	ds_read_b128 v[208:211], v152 offset:20480
	ds_read_b128 v[212:215], v152 offset:21504
	ds_read_b128 v[216:219], v152 offset:22528
	ds_read_b128 v[220:223], v152 offset:23552
	global_load_lds_dwordx4 v[224:225], off
	s_add_i32 m0, s77, 0x2000
	s_add_u32 s78, s72, 0x4000
	v_lshl_add_u64 v[224:225], s[72:73], 0, v[136:137]
	s_addc_u32 s79, s73, 0
	s_add_i32 s77, s62, s3
	global_load_lds_dwordx4 v[224:225], off
	v_lshl_add_u64 v[224:225], s[78:79], 0, v[132:133]
	s_mov_b32 m0, s77
	s_nop 0
	global_load_lds_dwordx4 v[224:225], off
	v_lshl_add_u64 v[224:225], s[78:79], 0, v[136:137]
	s_add_i32 m0, s77, 0x2000
	s_nop 0
	global_load_lds_dwordx4 v[224:225], off
	s_waitcnt vmcnt(6)
	s_waitcnt lgkmcnt(0)
	s_barrier
; #define PG8_STAGE(bufoff, gbase, voff) do { _Pragma("unroll") for (int _i = 0; _i < 2; ++_i) \
;         __builtin_amdgcn_global_load_lds((const unsigned*)((const char*)(gbase) + (voff)[_i]), (PG8_LAS unsigned*)(lds + (bufoff) + ldsw + _i * 8192), 16, 0, 0); } while (0)
; #define PG8_LDA(dst, b, h) do { _Pragma("unroll") for (int m = 0; m < 4; ++m) _Pragma("unroll") for (int k = 0; k < 2; ++k) dst[m][k] = *(const PG8_LAS bf16x8*)(lds + PG8_SA(b, h) + aoff + m * 2048 + k * 1024); } while (0)
; #define PG8_LDB(dst, b, h) do { _Pragma("unroll") for (int n = 0; n < 2; ++n) _Pragma("unroll") for (int k = 0; k < 2; ++k) dst[n][k] = *(const PG8_LAS bf16x8*)(lds + PG8_SB(b, h) + boff + n * 2048 + k * 1024); } while (0)
; #define PG8_MMA(ai, bj, At, Bt) do { __builtin_amdgcn_s_setprio(1); _Pragma("unroll") for (int m = 0; m < 4; ++m) _Pragma("unroll") for (int n = 0; n < 2; ++n) _Pragma("unroll") for (int k = 0; k < 2; ++k) \
;         acc[ai][bj][m][n] = __builtin_amdgcn_mfma_f32_16x16x32_bf16(Bt[n][k], At[m][k], acc[ai][bj][m][n], 0, 0, 0); __builtin_amdgcn_s_setprio(0); } while (0)
; #define PG8_WAIT_V(n) asm volatile("s_waitcnt vmcnt(" #n ")" ::: "memory")
; #define PG8_WAIT_L(n) asm volatile("s_waitcnt lgkmcnt(" #n ")" ::: "memory")
; #define PG8_BAR __builtin_amdgcn_s_barrier()
; #define PG8_SCHED __builtin_amdgcn_sched_barrier(0)
; template <class Epi, class Sched, bool ALIGN_EPI = false, bool SP2 = false>
; __device__ __forceinline__ void gemm_phase(PG8_LAS unsigned char* lds, const Gemm g, const Sched& S, const Epi& E) {
;     ...
;             PG8_WAIT_V(8); PG8_WAIT_L(0); PG8_BAR; PG8_MMA(1, 0, At, B0); PG8_MMA(1, 1, At, B1); PG8_BAR; PG8_SCHED;
;             PG8_LDB(B0, 1, 0); PG8_LDB(B1, 1, 1); PG8_SCHED; PG8_LDA(At, 1, 0); PG8_STAGE(PG8_SA(0, 1), a2 + hstep, voffA);
;             PG8_WAIT_V(8); PG8_WAIT_L(0); PG8_BAR; PG8_MMA(0, 0, At, B0); PG8_MMA(0, 1, At, B1); PG8_BAR; PG8_SCHED;
	s_setprio 1
	s_waitcnt lgkmcnt(0)
	v_mfma_f32_16x16x32_bf16 v[62:65], v[154:157], v[188:191], v[62:65]
	v_mfma_f32_16x16x32_bf16 v[62:65], v[158:161], v[196:199], v[62:65]
	v_mfma_f32_16x16x32_bf16 v[54:57], v[162:165], v[188:191], v[54:57]
	v_mfma_f32_16x16x32_bf16 v[54:57], v[166:169], v[196:199], v[54:57]
	v_mfma_f32_16x16x32_bf16 v[58:61], v[170:173], v[188:191], v[58:61]
	v_mfma_f32_16x16x32_bf16 v[58:61], v[174:177], v[196:199], v[58:61]
	v_mfma_f32_16x16x32_bf16 v[50:53], v[180:183], v[188:191], v[50:53]
	v_mfma_f32_16x16x32_bf16 v[50:53], v[184:187], v[196:199], v[50:53]
	v_mfma_f32_16x16x32_bf16 v[46:49], v[154:157], v[200:203], v[46:49]
	v_mfma_f32_16x16x32_bf16 v[46:49], v[158:161], v[204:207], v[46:49]
	v_mfma_f32_16x16x32_bf16 v[38:41], v[162:165], v[200:203], v[38:41]
	v_mfma_f32_16x16x32_bf16 v[38:41], v[166:169], v[204:207], v[38:41]
	v_mfma_f32_16x16x32_bf16 v[42:45], v[170:173], v[200:203], v[42:45]
	v_mfma_f32_16x16x32_bf16 v[42:45], v[174:177], v[204:207], v[42:45]
	v_mfma_f32_16x16x32_bf16 v[34:37], v[180:183], v[200:203], v[34:37]
	v_mfma_f32_16x16x32_bf16 v[34:37], v[184:187], v[204:207], v[34:37]
	s_setprio 0
	s_setprio 1
	v_mfma_f32_16x16x32_bf16 v[30:33], v[154:157], v[208:211], v[30:33]
	v_mfma_f32_16x16x32_bf16 v[30:33], v[158:161], v[212:215], v[30:33]
	v_mfma_f32_16x16x32_bf16 v[22:25], v[162:165], v[208:211], v[22:25]
	v_mfma_f32_16x16x32_bf16 v[22:25], v[166:169], v[212:215], v[22:25]
	v_mfma_f32_16x16x32_bf16 v[26:29], v[170:173], v[208:211], v[26:29]
	v_mfma_f32_16x16x32_bf16 v[26:29], v[174:177], v[212:215], v[26:29]
	v_mfma_f32_16x16x32_bf16 v[18:21], v[180:183], v[208:211], v[18:21]
	v_mfma_f32_16x16x32_bf16 v[18:21], v[184:187], v[212:215], v[18:21]
	v_mfma_f32_16x16x32_bf16 v[14:17], v[154:157], v[216:219], v[14:17]
	v_mfma_f32_16x16x32_bf16 v[14:17], v[158:161], v[220:223], v[14:17]
	v_mfma_f32_16x16x32_bf16 v[6:9], v[162:165], v[216:219], v[6:9]
	v_mfma_f32_16x16x32_bf16 v[6:9], v[166:169], v[220:223], v[6:9]
	v_mfma_f32_16x16x32_bf16 v[10:13], v[170:173], v[216:219], v[10:13]
	v_mfma_f32_16x16x32_bf16 v[10:13], v[174:177], v[220:223], v[10:13]
	v_mfma_f32_16x16x32_bf16 v[2:5], v[180:183], v[216:219], v[2:5]
	v_mfma_f32_16x16x32_bf16 v[2:5], v[184:187], v[220:223], v[2:5]
	s_setprio 0
	s_barrier
	s_add_i32 s77, 0, 0x18000
	v_add_u32_e32 v138, s77, v148
	s_add_i32 s78, 0, 0x1c000
	ds_read_b128 v[154:157], v138
	ds_read_b128 v[158:161], v138 offset:1024
	ds_read_b128 v[162:165], v138 offset:2048
	ds_read_b128 v[166:169], v138 offset:3072
	v_add_u32_e32 v138, s78, v148
	ds_read_b128 v[170:173], v138
	ds_read_b128 v[174:177], v138 offset:1024
	ds_read_b128 v[180:183], v138 offset:2048
	ds_read_b128 v[184:187], v138 offset:3072
	v_lshl_add_u64 v[224:225], s[74:75], 0, v[130:131]
	s_mov_b32 m0, s28
	s_nop 0
	global_load_lds_dwordx4 v[224:225], off
	v_lshl_add_u64 v[224:225], s[74:75], 0, v[134:135]
	s_mov_b32 m0, s29
	s_nop 0
	global_load_lds_dwordx4 v[224:225], off
	s_add_u32 s74, s74, 0x4000
	s_addc_u32 s75, s75, 0
	s_mov_b32 m0, s30
	v_lshl_add_u64 v[224:225], s[74:75], 0, v[130:131]
	ds_read_b128 v[188:191], v152 offset:32768
	ds_read_b128 v[196:199], v152 offset:33792
	ds_read_b128 v[200:203], v152 offset:34816
	ds_read_b128 v[204:207], v152 offset:35840
	ds_read_b128 v[208:211], v152 offset:36864
	ds_read_b128 v[212:215], v152 offset:37888
	ds_read_b128 v[216:219], v152 offset:38912
	ds_read_b128 v[220:223], v152 offset:39936
	global_load_lds_dwordx4 v[224:225], off
	v_lshl_add_u64 v[224:225], s[74:75], 0, v[134:135]
	s_mov_b32 m0, s31
	s_nop 0
	global_load_lds_dwordx4 v[224:225], off
	s_waitcnt vmcnt(8)
	s_waitcnt lgkmcnt(0)
	s_barrier
; #define PG8_STAGE(bufoff, gbase, voff) do { _Pragma("unroll") for (int _i = 0; _i < 2; ++_i) \
;         __builtin_amdgcn_global_load_lds((const unsigned*)((const char*)(gbase) + (voff)[_i]), (PG8_LAS unsigned*)(lds + (bufoff) + ldsw + _i * 8192), 16, 0, 0); } while (0)
; #define PG8_LDA(dst, b, h) do { _Pragma("unroll") for (int m = 0; m < 4; ++m) _Pragma("unroll") for (int k = 0; k < 2; ++k) dst[m][k] = *(const PG8_LAS bf16x8*)(lds + PG8_SA(b, h) + aoff + m * 2048 + k * 1024); } while (0)
; #define PG8_MMA(ai, bj, At, Bt) do { __builtin_amdgcn_s_setprio(1); _Pragma("unroll") for (int m = 0; m < 4; ++m) _Pragma("unroll") for (int n = 0; n < 2; ++n) _Pragma("unroll") for (int k = 0; k < 2; ++k) \
;         acc[ai][bj][m][n] = __builtin_amdgcn_mfma_f32_16x16x32_bf16(Bt[n][k], At[m][k], acc[ai][bj][m][n], 0, 0, 0); __builtin_amdgcn_s_setprio(0); } while (0)
; #define PG8_WAIT_V(n) asm volatile("s_waitcnt vmcnt(" #n ")" ::: "memory")
; #define PG8_WAIT_L(n) asm volatile("s_waitcnt lgkmcnt(" #n ")" ::: "memory")
; #define PG8_BAR __builtin_amdgcn_s_barrier()
; #define PG8_SCHED __builtin_amdgcn_sched_barrier(0)
; template <class Epi, class Sched, bool ALIGN_EPI = false, bool SP2 = false>
; __device__ __forceinline__ void gemm_phase(PG8_LAS unsigned char* lds, const Gemm g, const Sched& S, const Epi& E) {
;     ...
;             PG8_WAIT_V(8); PG8_WAIT_L(0); PG8_BAR; PG8_MMA(0, 0, At, B0); PG8_MMA(0, 1, At, B1); PG8_BAR; PG8_SCHED;
;             PG8_LDA(At, 1, 1); PG8_STAGE(PG8_SB(1, 0), b3, voffB); PG8_STAGE(PG8_SB(1, 1), b3 + hstep, voffB); PG8_STAGE(PG8_SA(1, 0), a3, voffA);
;             PG8_WAIT_V(8); PG8_WAIT_L(0); PG8_BAR; PG8_MMA(1, 0, At, B0); PG8_MMA(1, 1, At, B1); PG8_BAR; PG8_SCHED;
;     ...
;         }
;         if constexpr (Epi::HAS_MID) { if (seg == 0) E.mid(acc, cur, wr, wc, fr, fq); }
;         }
;         if constexpr (ALIGN_EPI) { if (wr == 0) PG8_BAR; }
	s_setprio 1
	s_waitcnt lgkmcnt(0)
	v_mfma_f32_16x16x32_bf16 v[126:129], v[154:157], v[188:191], v[126:129]
	v_mfma_f32_16x16x32_bf16 v[126:129], v[158:161], v[196:199], v[126:129]
	v_mfma_f32_16x16x32_bf16 v[118:121], v[162:165], v[188:191], v[118:121]
	v_mfma_f32_16x16x32_bf16 v[118:121], v[166:169], v[196:199], v[118:121]
	v_mfma_f32_16x16x32_bf16 v[122:125], v[170:173], v[188:191], v[122:125]
	v_mfma_f32_16x16x32_bf16 v[122:125], v[174:177], v[196:199], v[122:125]
	v_mfma_f32_16x16x32_bf16 v[114:117], v[180:183], v[188:191], v[114:117]
	v_mfma_f32_16x16x32_bf16 v[114:117], v[184:187], v[196:199], v[114:117]
	v_mfma_f32_16x16x32_bf16 v[110:113], v[154:157], v[200:203], v[110:113]
	v_mfma_f32_16x16x32_bf16 v[110:113], v[158:161], v[204:207], v[110:113]
	v_mfma_f32_16x16x32_bf16 v[102:105], v[162:165], v[200:203], v[102:105]
	v_mfma_f32_16x16x32_bf16 v[102:105], v[166:169], v[204:207], v[102:105]
	v_mfma_f32_16x16x32_bf16 v[106:109], v[170:173], v[200:203], v[106:109]
	v_mfma_f32_16x16x32_bf16 v[106:109], v[174:177], v[204:207], v[106:109]
	v_mfma_f32_16x16x32_bf16 v[98:101], v[180:183], v[200:203], v[98:101]
	v_mfma_f32_16x16x32_bf16 v[98:101], v[184:187], v[204:207], v[98:101]
	s_setprio 0
	s_setprio 1
	v_mfma_f32_16x16x32_bf16 v[94:97], v[154:157], v[208:211], v[94:97]
	v_mfma_f32_16x16x32_bf16 v[94:97], v[158:161], v[212:215], v[94:97]
	v_mfma_f32_16x16x32_bf16 v[86:89], v[162:165], v[208:211], v[86:89]
	v_mfma_f32_16x16x32_bf16 v[86:89], v[166:169], v[212:215], v[86:89]
	v_mfma_f32_16x16x32_bf16 v[90:93], v[170:173], v[208:211], v[90:93]
	v_mfma_f32_16x16x32_bf16 v[90:93], v[174:177], v[212:215], v[90:93]
	v_mfma_f32_16x16x32_bf16 v[82:85], v[180:183], v[208:211], v[82:85]
	v_mfma_f32_16x16x32_bf16 v[82:85], v[184:187], v[212:215], v[82:85]
	v_mfma_f32_16x16x32_bf16 v[78:81], v[154:157], v[216:219], v[78:81]
	v_mfma_f32_16x16x32_bf16 v[78:81], v[158:161], v[220:223], v[78:81]
	v_mfma_f32_16x16x32_bf16 v[70:73], v[162:165], v[216:219], v[70:73]
	v_mfma_f32_16x16x32_bf16 v[70:73], v[166:169], v[220:223], v[70:73]
	v_mfma_f32_16x16x32_bf16 v[74:77], v[170:173], v[216:219], v[74:77]
	v_mfma_f32_16x16x32_bf16 v[74:77], v[174:177], v[220:223], v[74:77]
	v_mfma_f32_16x16x32_bf16 v[66:69], v[180:183], v[216:219], v[66:69]
	v_mfma_f32_16x16x32_bf16 v[66:69], v[184:187], v[220:223], v[66:69]
	s_setprio 0
	s_barrier
	s_add_u32 s74, s72, 0x8000
	s_addc_u32 s75, s73, 0
	s_add_i32 s77, s77, s3
	v_lshl_add_u64 v[224:225], s[74:75], 0, v[132:133]
	s_mov_b32 m0, s77
	ds_read_b128 v[188:191], v152 offset:49152
	ds_read_b128 v[196:199], v152 offset:50176
	ds_read_b128 v[200:203], v152 offset:51200
	ds_read_b128 v[204:207], v152 offset:52224
	ds_read_b128 v[208:211], v152 offset:53248
	ds_read_b128 v[212:215], v152 offset:54272
	ds_read_b128 v[216:219], v152 offset:55296
	ds_read_b128 v[220:223], v152 offset:56320
	global_load_lds_dwordx4 v[224:225], off
	s_add_i32 m0, s77, 0x2000
	s_add_u32 s72, s72, 0xc000
	v_lshl_add_u64 v[224:225], s[74:75], 0, v[136:137]
	s_addc_u32 s73, s73, 0
	s_add_i32 s74, s78, s3
	global_load_lds_dwordx4 v[224:225], off
	v_lshl_add_u64 v[224:225], s[72:73], 0, v[132:133]
	s_mov_b32 m0, s74
	s_nop 0
	global_load_lds_dwordx4 v[224:225], off
	v_lshl_add_u64 v[224:225], s[72:73], 0, v[136:137]
	s_add_i32 m0, s74, 0x2000
	s_nop 0
	global_load_lds_dwordx4 v[224:225], off
	s_waitcnt vmcnt(6)
	s_waitcnt lgkmcnt(0)
	s_barrier
	s_setprio 1
	s_waitcnt lgkmcnt(0)
	v_mfma_f32_16x16x32_bf16 v[62:65], v[154:157], v[188:191], v[62:65]
	v_mfma_f32_16x16x32_bf16 v[62:65], v[158:161], v[196:199], v[62:65]
	v_mfma_f32_16x16x32_bf16 v[54:57], v[162:165], v[188:191], v[54:57]
	v_mfma_f32_16x16x32_bf16 v[54:57], v[166:169], v[196:199], v[54:57]
	v_mfma_f32_16x16x32_bf16 v[58:61], v[170:173], v[188:191], v[58:61]
	v_mfma_f32_16x16x32_bf16 v[58:61], v[174:177], v[196:199], v[58:61]
	v_mfma_f32_16x16x32_bf16 v[50:53], v[180:183], v[188:191], v[50:53]
	v_mfma_f32_16x16x32_bf16 v[50:53], v[184:187], v[196:199], v[50:53]
	v_mfma_f32_16x16x32_bf16 v[46:49], v[154:157], v[200:203], v[46:49]
	v_mfma_f32_16x16x32_bf16 v[46:49], v[158:161], v[204:207], v[46:49]
	v_mfma_f32_16x16x32_bf16 v[38:41], v[162:165], v[200:203], v[38:41]
	v_mfma_f32_16x16x32_bf16 v[38:41], v[166:169], v[204:207], v[38:41]
	v_mfma_f32_16x16x32_bf16 v[42:45], v[170:173], v[200:203], v[42:45]
	v_mfma_f32_16x16x32_bf16 v[42:45], v[174:177], v[204:207], v[42:45]
	v_mfma_f32_16x16x32_bf16 v[34:37], v[180:183], v[200:203], v[34:37]
	v_mfma_f32_16x16x32_bf16 v[34:37], v[184:187], v[204:207], v[34:37]
	s_setprio 0
	s_setprio 1
	v_mfma_f32_16x16x32_bf16 v[30:33], v[154:157], v[208:211], v[30:33]
	v_mfma_f32_16x16x32_bf16 v[30:33], v[158:161], v[212:215], v[30:33]
	v_mfma_f32_16x16x32_bf16 v[22:25], v[162:165], v[208:211], v[22:25]
	v_mfma_f32_16x16x32_bf16 v[22:25], v[166:169], v[212:215], v[22:25]
	v_mfma_f32_16x16x32_bf16 v[26:29], v[170:173], v[208:211], v[26:29]
	v_mfma_f32_16x16x32_bf16 v[26:29], v[174:177], v[212:215], v[26:29]
	v_mfma_f32_16x16x32_bf16 v[18:21], v[180:183], v[208:211], v[18:21]
	v_mfma_f32_16x16x32_bf16 v[18:21], v[184:187], v[212:215], v[18:21]
	v_mfma_f32_16x16x32_bf16 v[14:17], v[154:157], v[216:219], v[14:17]
	v_mfma_f32_16x16x32_bf16 v[14:17], v[158:161], v[220:223], v[14:17]
	v_mfma_f32_16x16x32_bf16 v[6:9], v[162:165], v[216:219], v[6:9]
	v_mfma_f32_16x16x32_bf16 v[6:9], v[166:169], v[220:223], v[6:9]
	v_mfma_f32_16x16x32_bf16 v[10:13], v[170:173], v[216:219], v[10:13]
	v_mfma_f32_16x16x32_bf16 v[10:13], v[174:177], v[220:223], v[10:13]
	v_mfma_f32_16x16x32_bf16 v[2:5], v[180:183], v[216:219], v[2:5]
	v_mfma_f32_16x16x32_bf16 v[2:5], v[184:187], v[220:223], v[2:5]
	s_setprio 0
	s_barrier
	s_add_i32 s76, s76, 2
	s_add_u32 s48, s48, 0x10000
	s_addc_u32 s49, s49, 0
	s_add_u32 s68, s68, 0x10000
	s_addc_u32 s69, s69, 0
	s_cmp_gt_u32 s76, 61
	s_cbranch_scc0 .LBB0_115
	s_and_b64 vcc, exec, s[14:15]
	s_cbranch_vccz .LBB0_118
	s_barrier

; #define PG8_STAGE(bufoff, gbase, voff) do { _Pragma("unroll") for (int _i = 0; _i < 2; ++_i) \
;         __builtin_amdgcn_global_load_lds((const unsigned*)((const char*)(gbase) + (voff)[_i]), (PG8_LAS unsigned*)(lds + (bufoff) + ldsw + _i * 8192), 16, 0, 0); } while (0)
; #define PG8_LDA(dst, b, h) do { _Pragma("unroll") for (int m = 0; m < 4; ++m) _Pragma("unroll") for (int k = 0; k < 2; ++k) dst[m][k] = *(const PG8_LAS bf16x8*)(lds + PG8_SA(b, h) + aoff + m * 2048 + k * 1024); } while (0)
; #define PG8_LDB(dst, b, h) do { _Pragma("unroll") for (int n = 0; n < 2; ++n) _Pragma("unroll") for (int k = 0; k < 2; ++k) dst[n][k] = *(const PG8_LAS bf16x8*)(lds + PG8_SB(b, h) + boff + n * 2048 + k * 1024); } while (0)
; #define PG8_MMA(ai, bj, At, Bt) do { __builtin_amdgcn_s_setprio(1); _Pragma("unroll") for (int m = 0; m < 4; ++m) _Pragma("unroll") for (int n = 0; n < 2; ++n) _Pragma("unroll") for (int k = 0; k < 2; ++k) \
;         acc[ai][bj][m][n] = __builtin_amdgcn_mfma_f32_16x16x32_bf16(Bt[n][k], At[m][k], acc[ai][bj][m][n], 0, 0, 0); __builtin_amdgcn_s_setprio(0); } while (0)
; #define PG8_WAIT_V(n) asm volatile("s_waitcnt vmcnt(" #n ")" ::: "memory")
; #define PG8_WAIT_L(n) asm volatile("s_waitcnt lgkmcnt(" #n ")" ::: "memory")
; template <class Epi, class Sched, bool ALIGN_EPI = false, bool SP2 = false>
; __device__ __forceinline__ void gemm_phase(PG8_LAS unsigned char* lds, const Gemm g, const Sched& S, const Epi& E) {
;     ...
;         for (; t < tend; t += 2) {
;             const bool last = (t == nt - 2);
;             const char* a1 = cA + (size_t)(t + 1) * kstep;
;             const char* a2 = last ? nA : cA + (size_t)(t + 2) * kstep; const char* b2 = last ? nB : cB + (size_t)(t + 2) * kstep;
;             const char* a3 = a2 + kstep; const char* b3 = b2 + kstep;
;             if (last && has_next) S.a_ready(nxt);
;             if constexpr (SP2) {
;             PG8_LDB(B0, 0, 0); PG8_LDB(B1, 0, 1); PG8_SCHED; PG8_LDA(At, 0, 0); PG8_STAGE(PG8_SA(1, 1), a1 + hstep, voffA);
;             PG8_WAIT_V(8); PG8_WAIT_L(0); PG8_BAR; PG8_MMA(0, 0, At, B0); PG8_MMA(0, 1, At, B1); PG8_BAR; PG8_SCHED;
;             PG8_LDA(At, 0, 1); PG8_STAGE(PG8_SB(0, 0), b2, voffB); PG8_STAGE(PG8_SB(0, 1), b2 + hstep, voffB); PG8_STAGE(PG8_SA(0, 0), a2, voffA);
;             PG8_WAIT_V(8); PG8_WAIT_L(0); PG8_BAR; PG8_MMA(1, 0, At, B0); PG8_MMA(1, 1, At, B1); PG8_BAR; PG8_SCHED;
.LBB0_200:
	ds_read_b128 v[148:151], v154
	ds_read_b128 v[158:161], v154 offset:1024
	ds_read_b128 v[162:165], v154 offset:2048
	ds_read_b128 v[166:169], v154 offset:3072
	ds_read_b128 v[170:173], v155
	ds_read_b128 v[174:177], v155 offset:1024
	ds_read_b128 v[180:183], v155 offset:2048
	ds_read_b128 v[184:187], v155 offset:3072
	s_add_u32 s46, s44, 0x4000
	s_addc_u32 s47, s45, 0
	s_cmpk_eq_i32 s76, 0xa8
	s_cselect_b32 s50, s6, s46
	s_cselect_b32 s51, s7, s47
	s_cselect_b32 s48, s24, s74
	s_cselect_b32 s49, s25, s75
	s_add_u32 s46, s50, 0x8000
	s_addc_u32 s47, s51, 0
	s_sub_u32 s46, s44, 0x4000
	s_subb_u32 s47, s45, 0
	v_lshl_add_u64 v[224:225], s[46:47], 0, v[130:131]
	s_mov_b32 m0, s57
	s_nop 0
	global_load_lds_dwordx4 v[224:225], off
	v_lshl_add_u64 v[224:225], s[46:47], 0, v[134:135]
	s_mov_b32 m0, s58
	s_nop 0
	global_load_lds_dwordx4 v[224:225], off
	v_lshl_add_u64 v[224:225], s[44:45], 0, v[140:141]
	s_add_i32 m0, s26, 0xc000
	ds_read_b128 v[188:191], v156
	ds_read_b128 v[196:199], v156 offset:1024
	ds_read_b128 v[200:203], v156 offset:2048
	ds_read_b128 v[204:207], v156 offset:3072
	ds_read_b128 v[208:211], v156 offset:4096
	ds_read_b128 v[212:215], v156 offset:5120
	ds_read_b128 v[216:219], v156 offset:6144
	ds_read_b128 v[220:223], v156 offset:7168
	global_load_lds_dwordx4 v[224:225], off
	v_lshl_add_u64 v[224:225], s[44:45], 0, v[142:143]
	s_add_i32 m0, s26, 0xe000
	s_nop 0
	global_load_lds_dwordx4 v[224:225], off
	s_waitcnt vmcnt(8)
	s_waitcnt lgkmcnt(0)
	s_barrier
	s_setprio 1
	s_waitcnt lgkmcnt(0)
	v_mfma_f32_16x16x32_bf16 v[126:129], v[148:151], v[188:191], v[126:129]
	v_mfma_f32_16x16x32_bf16 v[126:129], v[158:161], v[196:199], v[126:129]
	v_mfma_f32_16x16x32_bf16 v[122:125], v[162:165], v[188:191], v[122:125]
	v_mfma_f32_16x16x32_bf16 v[122:125], v[166:169], v[196:199], v[122:125]
	v_mfma_f32_16x16x32_bf16 v[118:121], v[170:173], v[188:191], v[118:121]
	v_mfma_f32_16x16x32_bf16 v[118:121], v[174:177], v[196:199], v[118:121]
	v_mfma_f32_16x16x32_bf16 v[114:117], v[180:183], v[188:191], v[114:117]
	v_mfma_f32_16x16x32_bf16 v[114:117], v[184:187], v[196:199], v[114:117]
	v_mfma_f32_16x16x32_bf16 v[110:113], v[148:151], v[200:203], v[110:113]
	v_mfma_f32_16x16x32_bf16 v[110:113], v[158:161], v[204:207], v[110:113]
	v_mfma_f32_16x16x32_bf16 v[106:109], v[162:165], v[200:203], v[106:109]
	v_mfma_f32_16x16x32_bf16 v[106:109], v[166:169], v[204:207], v[106:109]
	v_mfma_f32_16x16x32_bf16 v[102:105], v[170:173], v[200:203], v[102:105]
	v_mfma_f32_16x16x32_bf16 v[102:105], v[174:177], v[204:207], v[102:105]
	v_mfma_f32_16x16x32_bf16 v[98:101], v[180:183], v[200:203], v[98:101]
	v_mfma_f32_16x16x32_bf16 v[98:101], v[184:187], v[204:207], v[98:101]
	s_setprio 0
	s_setprio 1
	v_mfma_f32_16x16x32_bf16 v[94:97], v[148:151], v[208:211], v[94:97]
	v_mfma_f32_16x16x32_bf16 v[94:97], v[158:161], v[212:215], v[94:97]
	v_mfma_f32_16x16x32_bf16 v[90:93], v[162:165], v[208:211], v[90:93]
	v_mfma_f32_16x16x32_bf16 v[90:93], v[166:169], v[212:215], v[90:93]
	v_mfma_f32_16x16x32_bf16 v[86:89], v[170:173], v[208:211], v[86:89]
	v_mfma_f32_16x16x32_bf16 v[86:89], v[174:177], v[212:215], v[86:89]
	v_mfma_f32_16x16x32_bf16 v[82:85], v[180:183], v[208:211], v[82:85]
	v_mfma_f32_16x16x32_bf16 v[82:85], v[184:187], v[212:215], v[82:85]
	v_mfma_f32_16x16x32_bf16 v[78:81], v[148:151], v[216:219], v[78:81]
	v_mfma_f32_16x16x32_bf16 v[78:81], v[158:161], v[220:223], v[78:81]
	v_mfma_f32_16x16x32_bf16 v[74:77], v[162:165], v[216:219], v[74:77]
	v_mfma_f32_16x16x32_bf16 v[74:77], v[166:169], v[220:223], v[74:77]
	v_mfma_f32_16x16x32_bf16 v[70:73], v[170:173], v[216:219], v[70:73]
	v_mfma_f32_16x16x32_bf16 v[70:73], v[174:177], v[220:223], v[70:73]
	v_mfma_f32_16x16x32_bf16 v[66:69], v[180:183], v[216:219], v[66:69]
	v_mfma_f32_16x16x32_bf16 v[66:69], v[184:187], v[220:223], v[66:69]
	s_setprio 0
	s_barrier
	s_add_i32 s77, s59, s3
	v_lshl_add_u64 v[224:225], s[48:49], 0, v[132:133]
	s_mov_b32 m0, s77
	ds_read_b128 v[188:191], v156 offset:16384
	ds_read_b128 v[196:199], v156 offset:17408
	ds_read_b128 v[200:203], v156 offset:18432
	ds_read_b128 v[204:207], v156 offset:19456
	ds_read_b128 v[208:211], v156 offset:20480
	ds_read_b128 v[212:215], v156 offset:21504
	ds_read_b128 v[216:219], v156 offset:22528
	ds_read_b128 v[220:223], v156 offset:23552
	global_load_lds_dwordx4 v[224:225], off
	s_add_i32 m0, s77, 0x2000
	s_add_u32 s78, s48, 0x4000
	v_lshl_add_u64 v[224:225], s[48:49], 0, v[136:137]
	s_addc_u32 s79, s49, 0
	s_add_i32 s77, s61, s3
	global_load_lds_dwordx4 v[224:225], off
	v_lshl_add_u64 v[224:225], s[78:79], 0, v[132:133]
	s_mov_b32 m0, s77
	s_nop 0
	global_load_lds_dwordx4 v[224:225], off
	v_lshl_add_u64 v[224:225], s[78:79], 0, v[136:137]
	s_add_i32 m0, s77, 0x2000
	s_nop 0
	global_load_lds_dwordx4 v[224:225], off
	s_waitcnt vmcnt(6)
	s_waitcnt lgkmcnt(0)
	s_barrier
; #define PG8_STAGE(bufoff, gbase, voff) do { _Pragma("unroll") for (int _i = 0; _i < 2; ++_i) \
;         __builtin_amdgcn_global_load_lds((const unsigned*)((const char*)(gbase) + (voff)[_i]), (PG8_LAS unsigned*)(lds + (bufoff) + ldsw + _i * 8192), 16, 0, 0); } while (0)
; #define PG8_LDA(dst, b, h) do { _Pragma("unroll") for (int m = 0; m < 4; ++m) _Pragma("unroll") for (int k = 0; k < 2; ++k) dst[m][k] = *(const PG8_LAS bf16x8*)(lds + PG8_SA(b, h) + aoff + m * 2048 + k * 1024); } while (0)
; #define PG8_LDB(dst, b, h) do { _Pragma("unroll") for (int n = 0; n < 2; ++n) _Pragma("unroll") for (int k = 0; k < 2; ++k) dst[n][k] = *(const PG8_LAS bf16x8*)(lds + PG8_SB(b, h) + boff + n * 2048 + k * 1024); } while (0)
; #define PG8_MMA(ai, bj, At, Bt) do { __builtin_amdgcn_s_setprio(1); _Pragma("unroll") for (int m = 0; m < 4; ++m) _Pragma("unroll") for (int n = 0; n < 2; ++n) _Pragma("unroll") for (int k = 0; k < 2; ++k) \
;         acc[ai][bj][m][n] = __builtin_amdgcn_mfma_f32_16x16x32_bf16(Bt[n][k], At[m][k], acc[ai][bj][m][n], 0, 0, 0); __builtin_amdgcn_s_setprio(0); } while (0)
; #define PG8_WAIT_V(n) asm volatile("s_waitcnt vmcnt(" #n ")" ::: "memory")
; #define PG8_WAIT_L(n) asm volatile("s_waitcnt lgkmcnt(" #n ")" ::: "memory")
; #define PG8_BAR __builtin_amdgcn_s_barrier()
; #define PG8_SCHED __builtin_amdgcn_sched_barrier(0)
; template <class Epi, class Sched, bool ALIGN_EPI = false, bool SP2 = false>
; __device__ __forceinline__ void gemm_phase(PG8_LAS unsigned char* lds, const Gemm g, const Sched& S, const Epi& E) {
;     ...
;             PG8_WAIT_V(8); PG8_WAIT_L(0); PG8_BAR; PG8_MMA(1, 0, At, B0); PG8_MMA(1, 1, At, B1); PG8_BAR; PG8_SCHED;
;             PG8_LDB(B0, 1, 0); PG8_LDB(B1, 1, 1); PG8_SCHED; PG8_LDA(At, 1, 0); PG8_STAGE(PG8_SA(0, 1), a2 + hstep, voffA);
;             PG8_WAIT_V(8); PG8_WAIT_L(0); PG8_BAR; PG8_MMA(0, 0, At, B0); PG8_MMA(0, 1, At, B1); PG8_BAR; PG8_SCHED;
	s_setprio 1
	s_waitcnt lgkmcnt(0)
	v_mfma_f32_16x16x32_bf16 v[62:65], v[148:151], v[188:191], v[62:65]
	v_mfma_f32_16x16x32_bf16 v[62:65], v[158:161], v[196:199], v[62:65]
	v_mfma_f32_16x16x32_bf16 v[58:61], v[162:165], v[188:191], v[58:61]
	v_mfma_f32_16x16x32_bf16 v[58:61], v[166:169], v[196:199], v[58:61]
	v_mfma_f32_16x16x32_bf16 v[54:57], v[170:173], v[188:191], v[54:57]
	v_mfma_f32_16x16x32_bf16 v[54:57], v[174:177], v[196:199], v[54:57]
	v_mfma_f32_16x16x32_bf16 v[50:53], v[180:183], v[188:191], v[50:53]
	v_mfma_f32_16x16x32_bf16 v[50:53], v[184:187], v[196:199], v[50:53]
	v_mfma_f32_16x16x32_bf16 v[46:49], v[148:151], v[200:203], v[46:49]
	v_mfma_f32_16x16x32_bf16 v[46:49], v[158:161], v[204:207], v[46:49]
	v_mfma_f32_16x16x32_bf16 v[42:45], v[162:165], v[200:203], v[42:45]
	v_mfma_f32_16x16x32_bf16 v[42:45], v[166:169], v[204:207], v[42:45]
	v_mfma_f32_16x16x32_bf16 v[38:41], v[170:173], v[200:203], v[38:41]
	v_mfma_f32_16x16x32_bf16 v[38:41], v[174:177], v[204:207], v[38:41]
	v_mfma_f32_16x16x32_bf16 v[34:37], v[180:183], v[200:203], v[34:37]
	v_mfma_f32_16x16x32_bf16 v[34:37], v[184:187], v[204:207], v[34:37]
	s_setprio 0
	s_setprio 1
	v_mfma_f32_16x16x32_bf16 v[30:33], v[148:151], v[208:211], v[30:33]
	v_mfma_f32_16x16x32_bf16 v[30:33], v[158:161], v[212:215], v[30:33]
	v_mfma_f32_16x16x32_bf16 v[26:29], v[162:165], v[208:211], v[26:29]
	v_mfma_f32_16x16x32_bf16 v[26:29], v[166:169], v[212:215], v[26:29]
	v_mfma_f32_16x16x32_bf16 v[22:25], v[170:173], v[208:211], v[22:25]
	v_mfma_f32_16x16x32_bf16 v[22:25], v[174:177], v[212:215], v[22:25]
	v_mfma_f32_16x16x32_bf16 v[18:21], v[180:183], v[208:211], v[18:21]
	v_mfma_f32_16x16x32_bf16 v[18:21], v[184:187], v[212:215], v[18:21]
	v_mfma_f32_16x16x32_bf16 v[14:17], v[148:151], v[216:219], v[14:17]
	v_mfma_f32_16x16x32_bf16 v[14:17], v[158:161], v[220:223], v[14:17]
	v_mfma_f32_16x16x32_bf16 v[10:13], v[162:165], v[216:219], v[10:13]
	v_mfma_f32_16x16x32_bf16 v[10:13], v[166:169], v[220:223], v[10:13]
	v_mfma_f32_16x16x32_bf16 v[6:9], v[170:173], v[216:219], v[6:9]
	v_mfma_f32_16x16x32_bf16 v[6:9], v[174:177], v[220:223], v[6:9]
	v_mfma_f32_16x16x32_bf16 v[2:5], v[180:183], v[216:219], v[2:5]
	v_mfma_f32_16x16x32_bf16 v[2:5], v[184:187], v[220:223], v[2:5]
	s_setprio 0
	s_barrier
	s_add_i32 s77, 0, 0x18000
	v_add_u32_e32 v138, s77, v153
	s_add_i32 s78, 0, 0x1c000
	ds_read_b128 v[148:151], v138
	ds_read_b128 v[158:161], v138 offset:1024
	ds_read_b128 v[162:165], v138 offset:2048
	ds_read_b128 v[166:169], v138 offset:3072
	v_add_u32_e32 v138, s78, v153
	ds_read_b128 v[170:173], v138
	ds_read_b128 v[174:177], v138 offset:1024
	ds_read_b128 v[180:183], v138 offset:2048
	ds_read_b128 v[184:187], v138 offset:3072
	v_lshl_add_u64 v[224:225], s[50:51], 0, v[130:131]
	s_mov_b32 m0, s26
	s_nop 0
	global_load_lds_dwordx4 v[224:225], off
	v_lshl_add_u64 v[224:225], s[50:51], 0, v[134:135]
	s_mov_b32 m0, s27
	s_nop 0
	global_load_lds_dwordx4 v[224:225], off
	s_add_u32 s50, s50, 0x4000
	s_addc_u32 s51, s51, 0
	s_mov_b32 m0, s28
	v_lshl_add_u64 v[224:225], s[50:51], 0, v[130:131]
	ds_read_b128 v[188:191], v156 offset:32768
	ds_read_b128 v[196:199], v156 offset:33792
	ds_read_b128 v[200:203], v156 offset:34816
	ds_read_b128 v[204:207], v156 offset:35840
	ds_read_b128 v[208:211], v156 offset:36864
	ds_read_b128 v[212:215], v156 offset:37888
	ds_read_b128 v[216:219], v156 offset:38912
	ds_read_b128 v[220:223], v156 offset:39936
	global_load_lds_dwordx4 v[224:225], off
	v_lshl_add_u64 v[224:225], s[50:51], 0, v[134:135]
	s_mov_b32 m0, s29
	s_nop 0
	global_load_lds_dwordx4 v[224:225], off
	s_waitcnt vmcnt(8)
	s_waitcnt lgkmcnt(0)
	s_barrier
; #define PG8_STAGE(bufoff, gbase, voff) do { _Pragma("unroll") for (int _i = 0; _i < 2; ++_i) \
;         __builtin_amdgcn_global_load_lds((const unsigned*)((const char*)(gbase) + (voff)[_i]), (PG8_LAS unsigned*)(lds + (bufoff) + ldsw + _i * 8192), 16, 0, 0); } while (0)
; #define PG8_LDA(dst, b, h) do { _Pragma("unroll") for (int m = 0; m < 4; ++m) _Pragma("unroll") for (int k = 0; k < 2; ++k) dst[m][k] = *(const PG8_LAS bf16x8*)(lds + PG8_SA(b, h) + aoff + m * 2048 + k * 1024); } while (0)
; #define PG8_MMA(ai, bj, At, Bt) do { __builtin_amdgcn_s_setprio(1); _Pragma("unroll") for (int m = 0; m < 4; ++m) _Pragma("unroll") for (int n = 0; n < 2; ++n) _Pragma("unroll") for (int k = 0; k < 2; ++k) \
;         acc[ai][bj][m][n] = __builtin_amdgcn_mfma_f32_16x16x32_bf16(Bt[n][k], At[m][k], acc[ai][bj][m][n], 0, 0, 0); __builtin_amdgcn_s_setprio(0); } while (0)
; #define PG8_WAIT_V(n) asm volatile("s_waitcnt vmcnt(" #n ")" ::: "memory")
; #define PG8_WAIT_L(n) asm volatile("s_waitcnt lgkmcnt(" #n ")" ::: "memory")
; #define PG8_BAR __builtin_amdgcn_s_barrier()
; #define PG8_SCHED __builtin_amdgcn_sched_barrier(0)
; template <class Epi, class Sched, bool ALIGN_EPI = false, bool SP2 = false>
; __device__ __forceinline__ void gemm_phase(PG8_LAS unsigned char* lds, const Gemm g, const Sched& S, const Epi& E) {
;     ...
;             PG8_WAIT_V(8); PG8_WAIT_L(0); PG8_BAR; PG8_MMA(0, 0, At, B0); PG8_MMA(0, 1, At, B1); PG8_BAR; PG8_SCHED;
;             PG8_LDA(At, 1, 1); PG8_STAGE(PG8_SB(1, 0), b3, voffB); PG8_STAGE(PG8_SB(1, 1), b3 + hstep, voffB); PG8_STAGE(PG8_SA(1, 0), a3, voffA);
;             PG8_WAIT_V(8); PG8_WAIT_L(0); PG8_BAR; PG8_MMA(1, 0, At, B0); PG8_MMA(1, 1, At, B1); PG8_BAR; PG8_SCHED;
;     ...
;         }
;         if constexpr (Epi::HAS_MID) { if (seg == 0) E.mid(acc, cur, wr, wc, fr, fq); }
;         }
;         if constexpr (ALIGN_EPI) { if (wr == 0) PG8_BAR; }
	s_setprio 1
	s_waitcnt lgkmcnt(0)
	v_mfma_f32_16x16x32_bf16 v[126:129], v[148:151], v[188:191], v[126:129]
	v_mfma_f32_16x16x32_bf16 v[126:129], v[158:161], v[196:199], v[126:129]
	v_mfma_f32_16x16x32_bf16 v[122:125], v[162:165], v[188:191], v[122:125]
	v_mfma_f32_16x16x32_bf16 v[122:125], v[166:169], v[196:199], v[122:125]
	v_mfma_f32_16x16x32_bf16 v[118:121], v[170:173], v[188:191], v[118:121]
	v_mfma_f32_16x16x32_bf16 v[118:121], v[174:177], v[196:199], v[118:121]
	v_mfma_f32_16x16x32_bf16 v[114:117], v[180:183], v[188:191], v[114:117]
	v_mfma_f32_16x16x32_bf16 v[114:117], v[184:187], v[196:199], v[114:117]
	v_mfma_f32_16x16x32_bf16 v[110:113], v[148:151], v[200:203], v[110:113]
	v_mfma_f32_16x16x32_bf16 v[110:113], v[158:161], v[204:207], v[110:113]
	v_mfma_f32_16x16x32_bf16 v[106:109], v[162:165], v[200:203], v[106:109]
	v_mfma_f32_16x16x32_bf16 v[106:109], v[166:169], v[204:207], v[106:109]
	v_mfma_f32_16x16x32_bf16 v[102:105], v[170:173], v[200:203], v[102:105]
	v_mfma_f32_16x16x32_bf16 v[102:105], v[174:177], v[204:207], v[102:105]
	v_mfma_f32_16x16x32_bf16 v[98:101], v[180:183], v[200:203], v[98:101]
	v_mfma_f32_16x16x32_bf16 v[98:101], v[184:187], v[204:207], v[98:101]
	s_setprio 0
	s_setprio 1
	v_mfma_f32_16x16x32_bf16 v[94:97], v[148:151], v[208:211], v[94:97]
	v_mfma_f32_16x16x32_bf16 v[94:97], v[158:161], v[212:215], v[94:97]
	v_mfma_f32_16x16x32_bf16 v[90:93], v[162:165], v[208:211], v[90:93]
	v_mfma_f32_16x16x32_bf16 v[90:93], v[166:169], v[212:215], v[90:93]
	v_mfma_f32_16x16x32_bf16 v[86:89], v[170:173], v[208:211], v[86:89]
	v_mfma_f32_16x16x32_bf16 v[86:89], v[174:177], v[212:215], v[86:89]
	v_mfma_f32_16x16x32_bf16 v[82:85], v[180:183], v[208:211], v[82:85]
	v_mfma_f32_16x16x32_bf16 v[82:85], v[184:187], v[212:215], v[82:85]
	v_mfma_f32_16x16x32_bf16 v[78:81], v[148:151], v[216:219], v[78:81]
	v_mfma_f32_16x16x32_bf16 v[78:81], v[158:161], v[220:223], v[78:81]
	v_mfma_f32_16x16x32_bf16 v[74:77], v[162:165], v[216:219], v[74:77]
	v_mfma_f32_16x16x32_bf16 v[74:77], v[166:169], v[220:223], v[74:77]
	v_mfma_f32_16x16x32_bf16 v[70:73], v[170:173], v[216:219], v[70:73]
	v_mfma_f32_16x16x32_bf16 v[70:73], v[174:177], v[220:223], v[70:73]
	v_mfma_f32_16x16x32_bf16 v[66:69], v[180:183], v[216:219], v[66:69]
	v_mfma_f32_16x16x32_bf16 v[66:69], v[184:187], v[220:223], v[66:69]
	s_setprio 0
	s_barrier
	s_add_u32 s50, s48, 0x8000
	s_addc_u32 s51, s49, 0
	s_add_i32 s77, s77, s3
	v_lshl_add_u64 v[224:225], s[50:51], 0, v[132:133]
	s_mov_b32 m0, s77
	ds_read_b128 v[188:191], v156 offset:49152
	ds_read_b128 v[196:199], v156 offset:50176
	ds_read_b128 v[200:203], v156 offset:51200
	ds_read_b128 v[204:207], v156 offset:52224
	ds_read_b128 v[208:211], v156 offset:53248
	ds_read_b128 v[212:215], v156 offset:54272
	ds_read_b128 v[216:219], v156 offset:55296
	ds_read_b128 v[220:223], v156 offset:56320
	global_load_lds_dwordx4 v[224:225], off
	s_add_i32 m0, s77, 0x2000
	s_add_u32 s48, s48, 0xc000
	v_lshl_add_u64 v[224:225], s[50:51], 0, v[136:137]
	s_addc_u32 s49, s49, 0
	s_add_i32 s50, s78, s3
	global_load_lds_dwordx4 v[224:225], off
	v_lshl_add_u64 v[224:225], s[48:49], 0, v[132:133]
	s_mov_b32 m0, s50
	s_nop 0
	global_load_lds_dwordx4 v[224:225], off
	v_lshl_add_u64 v[224:225], s[48:49], 0, v[136:137]
	s_add_i32 m0, s50, 0x2000
	s_nop 0
	global_load_lds_dwordx4 v[224:225], off
	s_waitcnt vmcnt(6)
	s_waitcnt lgkmcnt(0)
	s_barrier
	s_setprio 1
	s_waitcnt lgkmcnt(0)
	v_mfma_f32_16x16x32_bf16 v[62:65], v[148:151], v[188:191], v[62:65]
	v_mfma_f32_16x16x32_bf16 v[62:65], v[158:161], v[196:199], v[62:65]
	v_mfma_f32_16x16x32_bf16 v[58:61], v[162:165], v[188:191], v[58:61]
	v_mfma_f32_16x16x32_bf16 v[58:61], v[166:169], v[196:199], v[58:61]
	v_mfma_f32_16x16x32_bf16 v[54:57], v[170:173], v[188:191], v[54:57]
	v_mfma_f32_16x16x32_bf16 v[54:57], v[174:177], v[196:199], v[54:57]
	v_mfma_f32_16x16x32_bf16 v[50:53], v[180:183], v[188:191], v[50:53]
	v_mfma_f32_16x16x32_bf16 v[50:53], v[184:187], v[196:199], v[50:53]
	v_mfma_f32_16x16x32_bf16 v[46:49], v[148:151], v[200:203], v[46:49]
	v_mfma_f32_16x16x32_bf16 v[46:49], v[158:161], v[204:207], v[46:49]
	v_mfma_f32_16x16x32_bf16 v[42:45], v[162:165], v[200:203], v[42:45]
	v_mfma_f32_16x16x32_bf16 v[42:45], v[166:169], v[204:207], v[42:45]
	v_mfma_f32_16x16x32_bf16 v[38:41], v[170:173], v[200:203], v[38:41]
	v_mfma_f32_16x16x32_bf16 v[38:41], v[174:177], v[204:207], v[38:41]
	v_mfma_f32_16x16x32_bf16 v[34:37], v[180:183], v[200:203], v[34:37]
	v_mfma_f32_16x16x32_bf16 v[34:37], v[184:187], v[204:207], v[34:37]
	s_setprio 0
	s_setprio 1
	v_mfma_f32_16x16x32_bf16 v[30:33], v[148:151], v[208:211], v[30:33]
	v_mfma_f32_16x16x32_bf16 v[30:33], v[158:161], v[212:215], v[30:33]
	v_mfma_f32_16x16x32_bf16 v[26:29], v[162:165], v[208:211], v[26:29]
	v_mfma_f32_16x16x32_bf16 v[26:29], v[166:169], v[212:215], v[26:29]
	v_mfma_f32_16x16x32_bf16 v[22:25], v[170:173], v[208:211], v[22:25]
	v_mfma_f32_16x16x32_bf16 v[22:25], v[174:177], v[212:215], v[22:25]
	v_mfma_f32_16x16x32_bf16 v[18:21], v[180:183], v[208:211], v[18:21]
	v_mfma_f32_16x16x32_bf16 v[18:21], v[184:187], v[212:215], v[18:21]
	v_mfma_f32_16x16x32_bf16 v[14:17], v[148:151], v[216:219], v[14:17]
	v_mfma_f32_16x16x32_bf16 v[14:17], v[158:161], v[220:223], v[14:17]
	v_mfma_f32_16x16x32_bf16 v[10:13], v[162:165], v[216:219], v[10:13]
	v_mfma_f32_16x16x32_bf16 v[10:13], v[166:169], v[220:223], v[10:13]
	v_mfma_f32_16x16x32_bf16 v[6:9], v[170:173], v[216:219], v[6:9]
	v_mfma_f32_16x16x32_bf16 v[6:9], v[174:177], v[220:223], v[6:9]
	v_mfma_f32_16x16x32_bf16 v[2:5], v[180:183], v[216:219], v[2:5]
	v_mfma_f32_16x16x32_bf16 v[2:5], v[184:187], v[220:223], v[2:5]
	s_setprio 0
	s_barrier
	s_add_i32 s76, s76, 2
	s_add_u32 s44, s44, 0x10000
	s_addc_u32 s45, s45, 0
	s_add_u32 s74, s74, 0x10000
	s_addc_u32 s75, s75, 0
	s_cmpk_gt_u32 s76, 0xa9
	s_cbranch_scc0 .LBB0_200
	s_and_b64 vcc, exec, s[18:19]
	s_cbranch_vccz .LBB0_203
	s_barrier

; #define PG8_STAGE(bufoff, gbase, voff) do { _Pragma("unroll") for (int _i = 0; _i < 2; ++_i) \
;         __builtin_amdgcn_global_load_lds((const unsigned*)((const char*)(gbase) + (voff)[_i]), (PG8_LAS unsigned*)(lds + (bufoff) + ldsw + _i * 8192), 16, 0, 0); } while (0)
; #define PG8_LDA(dst, b, h) do { _Pragma("unroll") for (int m = 0; m < 4; ++m) _Pragma("unroll") for (int k = 0; k < 2; ++k) dst[m][k] = *(const PG8_LAS bf16x8*)(lds + PG8_SA(b, h) + aoff + m * 2048 + k * 1024); } while (0)
; #define PG8_LDB(dst, b, h) do { _Pragma("unroll") for (int n = 0; n < 2; ++n) _Pragma("unroll") for (int k = 0; k < 2; ++k) dst[n][k] = *(const PG8_LAS bf16x8*)(lds + PG8_SB(b, h) + boff + n * 2048 + k * 1024); } while (0)
; #define PG8_MMA(ai, bj, At, Bt) do { __builtin_amdgcn_s_setprio(1); _Pragma("unroll") for (int m = 0; m < 4; ++m) _Pragma("unroll") for (int n = 0; n < 2; ++n) _Pragma("unroll") for (int k = 0; k < 2; ++k) \
;         acc[ai][bj][m][n] = __builtin_amdgcn_mfma_f32_16x16x32_bf16(Bt[n][k], At[m][k], acc[ai][bj][m][n], 0, 0, 0); __builtin_amdgcn_s_setprio(0); } while (0)
; #define PG8_WAIT_V(n) asm volatile("s_waitcnt vmcnt(" #n ")" ::: "memory")
; #define PG8_WAIT_L(n) asm volatile("s_waitcnt lgkmcnt(" #n ")" ::: "memory")
; template <class Epi, class Sched, bool ALIGN_EPI = false, bool SP2 = false>
; __device__ __forceinline__ void gemm_phase(PG8_LAS unsigned char* lds, const Gemm g, const Sched& S, const Epi& E) {
;     ...
;         for (; t < tend; t += 2) {
;             const bool last = (t == nt - 2);
;             const char* a1 = cA + (size_t)(t + 1) * kstep;
;             const char* a2 = last ? nA : cA + (size_t)(t + 2) * kstep; const char* b2 = last ? nB : cB + (size_t)(t + 2) * kstep;
;             const char* a3 = a2 + kstep; const char* b3 = b2 + kstep;
;             if (last && has_next) S.a_ready(nxt);
;             if constexpr (SP2) {
;             PG8_LDB(B0, 0, 0); PG8_LDB(B1, 0, 1); PG8_SCHED; PG8_LDA(At, 0, 0); PG8_STAGE(PG8_SA(1, 1), a1 + hstep, voffA);
;             PG8_WAIT_V(8); PG8_WAIT_L(0); PG8_BAR; PG8_MMA(0, 0, At, B0); PG8_MMA(0, 1, At, B1); PG8_BAR; PG8_SCHED;
;             PG8_LDA(At, 0, 1); PG8_STAGE(PG8_SB(0, 0), b2, voffB); PG8_STAGE(PG8_SB(0, 1), b2 + hstep, voffB); PG8_STAGE(PG8_SA(0, 0), a2, voffA);
;             PG8_WAIT_V(8); PG8_WAIT_L(0); PG8_BAR; PG8_MMA(1, 0, At, B0); PG8_MMA(1, 1, At, B1); PG8_BAR; PG8_SCHED;
.LBB0_290:
	ds_read_b128 v[146:149], v162
	ds_read_b128 v[150:153], v162 offset:1024
	ds_read_b128 v[154:157], v162 offset:2048
	ds_read_b128 v[168:171], v162 offset:3072
	ds_read_b128 v[172:175], v163
	ds_read_b128 v[180:183], v163 offset:1024
	ds_read_b128 v[184:187], v163 offset:2048
	ds_read_b128 v[188:191], v163 offset:3072
	s_add_u32 s59, s72, 0x4000
	s_addc_u32 s62, s73, 0
	s_cmp_eq_u32 s58, 60
	s_cselect_b32 s78, s19, s59
	s_cselect_b32 s79, s5, s62
	s_cselect_b32 s76, s26, s33
	s_cselect_b32 s77, s17, s56
	s_add_u32 s74, s78, 0x8000
	s_addc_u32 s75, s79, 0
	s_sub_u32 s74, s72, 0x4000
	s_subb_u32 s75, s73, 0
	v_lshl_add_u64 v[158:159], s[74:75], 0, v[130:131]
	s_mov_b32 m0, s51
	s_nop 0
	global_load_lds_dwordx4 v[158:159], off
	v_lshl_add_u64 v[158:159], s[74:75], 0, v[134:135]
	s_mov_b32 m0, s57
	s_nop 0
	global_load_lds_dwordx4 v[158:159], off
	v_lshl_add_u64 v[158:159], s[72:73], 0, v[138:139]
	s_add_i32 m0, s15, 0xc000
	ds_read_b128 v[198:201], v164
	ds_read_b128 v[202:205], v164 offset:1024
	ds_read_b128 v[206:209], v164 offset:2048
	ds_read_b128 v[210:213], v164 offset:3072
	ds_read_b128 v[214:217], v164 offset:4096
	ds_read_b128 v[218:221], v164 offset:5120
	ds_read_b128 v[222:225], v164 offset:6144
	ds_read_b128 v[226:229], v164 offset:7168
	global_load_lds_dwordx4 v[158:159], off
	v_lshl_add_u64 v[158:159], s[72:73], 0, v[140:141]
	s_add_i32 m0, s15, 0xe000
	s_nop 0
	global_load_lds_dwordx4 v[158:159], off
	s_waitcnt vmcnt(8)
	s_waitcnt lgkmcnt(0)
	s_barrier
	s_setprio 1
	s_waitcnt lgkmcnt(0)
	v_mfma_f32_16x16x32_bf16 v[126:129], v[146:149], v[198:201], v[126:129]
	v_mfma_f32_16x16x32_bf16 v[126:129], v[150:153], v[202:205], v[126:129]
	v_mfma_f32_16x16x32_bf16 v[122:125], v[154:157], v[198:201], v[122:125]
	v_mfma_f32_16x16x32_bf16 v[122:125], v[168:171], v[202:205], v[122:125]
	v_mfma_f32_16x16x32_bf16 v[118:121], v[172:175], v[198:201], v[118:121]
	v_mfma_f32_16x16x32_bf16 v[118:121], v[180:183], v[202:205], v[118:121]
	v_mfma_f32_16x16x32_bf16 v[114:117], v[184:187], v[198:201], v[114:117]
	v_mfma_f32_16x16x32_bf16 v[114:117], v[188:191], v[202:205], v[114:117]
	v_mfma_f32_16x16x32_bf16 v[110:113], v[146:149], v[206:209], v[110:113]
	v_mfma_f32_16x16x32_bf16 v[110:113], v[150:153], v[210:213], v[110:113]
	v_mfma_f32_16x16x32_bf16 v[106:109], v[154:157], v[206:209], v[106:109]
	v_mfma_f32_16x16x32_bf16 v[106:109], v[168:171], v[210:213], v[106:109]
	v_mfma_f32_16x16x32_bf16 v[102:105], v[172:175], v[206:209], v[102:105]
	v_mfma_f32_16x16x32_bf16 v[102:105], v[180:183], v[210:213], v[102:105]
	v_mfma_f32_16x16x32_bf16 v[98:101], v[184:187], v[206:209], v[98:101]
	v_mfma_f32_16x16x32_bf16 v[98:101], v[188:191], v[210:213], v[98:101]
	s_setprio 0
	s_setprio 1
	v_mfma_f32_16x16x32_bf16 v[94:97], v[146:149], v[214:217], v[94:97]
	v_mfma_f32_16x16x32_bf16 v[94:97], v[150:153], v[218:221], v[94:97]
	v_mfma_f32_16x16x32_bf16 v[90:93], v[154:157], v[214:217], v[90:93]
	v_mfma_f32_16x16x32_bf16 v[90:93], v[168:171], v[218:221], v[90:93]
	v_mfma_f32_16x16x32_bf16 v[86:89], v[172:175], v[214:217], v[86:89]
	v_mfma_f32_16x16x32_bf16 v[86:89], v[180:183], v[218:221], v[86:89]
	v_mfma_f32_16x16x32_bf16 v[82:85], v[184:187], v[214:217], v[82:85]
	v_mfma_f32_16x16x32_bf16 v[82:85], v[188:191], v[218:221], v[82:85]
	v_mfma_f32_16x16x32_bf16 v[78:81], v[146:149], v[222:225], v[78:81]
	v_mfma_f32_16x16x32_bf16 v[78:81], v[150:153], v[226:229], v[78:81]
	v_mfma_f32_16x16x32_bf16 v[74:77], v[154:157], v[222:225], v[74:77]
	v_mfma_f32_16x16x32_bf16 v[74:77], v[168:171], v[226:229], v[74:77]
	v_mfma_f32_16x16x32_bf16 v[70:73], v[172:175], v[222:225], v[70:73]
	v_mfma_f32_16x16x32_bf16 v[70:73], v[180:183], v[226:229], v[70:73]
	v_mfma_f32_16x16x32_bf16 v[66:69], v[184:187], v[222:225], v[66:69]
	v_mfma_f32_16x16x32_bf16 v[66:69], v[188:191], v[226:229], v[66:69]
	s_setprio 0
	s_barrier
	s_add_i32 s59, s81, s3
	v_lshl_add_u64 v[158:159], s[76:77], 0, v[132:133]
	s_mov_b32 m0, s59
	ds_read_b128 v[198:201], v164 offset:16384
	ds_read_b128 v[202:205], v164 offset:17408
	ds_read_b128 v[206:209], v164 offset:18432
	ds_read_b128 v[210:213], v164 offset:19456
	ds_read_b128 v[214:217], v164 offset:20480
	ds_read_b128 v[218:221], v164 offset:21504
	ds_read_b128 v[222:225], v164 offset:22528
	ds_read_b128 v[226:229], v164 offset:23552
	global_load_lds_dwordx4 v[158:159], off
	s_add_i32 m0, s59, 0x2000
	s_add_u32 s62, s76, 0x4000
	v_lshl_add_u64 v[158:159], s[76:77], 0, v[136:137]
	s_addc_u32 s63, s77, 0
	s_add_i32 s59, s82, s3
	global_load_lds_dwordx4 v[158:159], off
	v_lshl_add_u64 v[158:159], s[62:63], 0, v[132:133]
	s_mov_b32 m0, s59
	s_nop 0
	global_load_lds_dwordx4 v[158:159], off
	v_lshl_add_u64 v[158:159], s[62:63], 0, v[136:137]
	s_add_i32 m0, s59, 0x2000
	s_nop 0
	global_load_lds_dwordx4 v[158:159], off
	s_waitcnt vmcnt(6)
	s_waitcnt lgkmcnt(0)
	s_barrier
; #define PG8_STAGE(bufoff, gbase, voff) do { _Pragma("unroll") for (int _i = 0; _i < 2; ++_i) \
;         __builtin_amdgcn_global_load_lds((const unsigned*)((const char*)(gbase) + (voff)[_i]), (PG8_LAS unsigned*)(lds + (bufoff) + ldsw + _i * 8192), 16, 0, 0); } while (0)
; #define PG8_LDA(dst, b, h) do { _Pragma("unroll") for (int m = 0; m < 4; ++m) _Pragma("unroll") for (int k = 0; k < 2; ++k) dst[m][k] = *(const PG8_LAS bf16x8*)(lds + PG8_SA(b, h) + aoff + m * 2048 + k * 1024); } while (0)
; #define PG8_LDB(dst, b, h) do { _Pragma("unroll") for (int n = 0; n < 2; ++n) _Pragma("unroll") for (int k = 0; k < 2; ++k) dst[n][k] = *(const PG8_LAS bf16x8*)(lds + PG8_SB(b, h) + boff + n * 2048 + k * 1024); } while (0)
; #define PG8_MMA(ai, bj, At, Bt) do { __builtin_amdgcn_s_setprio(1); _Pragma("unroll") for (int m = 0; m < 4; ++m) _Pragma("unroll") for (int n = 0; n < 2; ++n) _Pragma("unroll") for (int k = 0; k < 2; ++k) \
;         acc[ai][bj][m][n] = __builtin_amdgcn_mfma_f32_16x16x32_bf16(Bt[n][k], At[m][k], acc[ai][bj][m][n], 0, 0, 0); __builtin_amdgcn_s_setprio(0); } while (0)
; #define PG8_WAIT_V(n) asm volatile("s_waitcnt vmcnt(" #n ")" ::: "memory")
; #define PG8_WAIT_L(n) asm volatile("s_waitcnt lgkmcnt(" #n ")" ::: "memory")
; #define PG8_BAR __builtin_amdgcn_s_barrier()
; #define PG8_SCHED __builtin_amdgcn_sched_barrier(0)
; template <class Epi, class Sched, bool ALIGN_EPI = false, bool SP2 = false>
; __device__ __forceinline__ void gemm_phase(PG8_LAS unsigned char* lds, const Gemm g, const Sched& S, const Epi& E) {
;     ...
;             PG8_WAIT_V(8); PG8_WAIT_L(0); PG8_BAR; PG8_MMA(1, 0, At, B0); PG8_MMA(1, 1, At, B1); PG8_BAR; PG8_SCHED;
;             PG8_LDB(B0, 1, 0); PG8_LDB(B1, 1, 1); PG8_SCHED; PG8_LDA(At, 1, 0); PG8_STAGE(PG8_SA(0, 1), a2 + hstep, voffA);
;             PG8_WAIT_V(8); PG8_WAIT_L(0); PG8_BAR; PG8_MMA(0, 0, At, B0); PG8_MMA(0, 1, At, B1); PG8_BAR; PG8_SCHED;
	s_setprio 1
	s_waitcnt lgkmcnt(0)
	v_mfma_f32_16x16x32_bf16 v[62:65], v[146:149], v[198:201], v[62:65]
	v_mfma_f32_16x16x32_bf16 v[62:65], v[150:153], v[202:205], v[62:65]
	v_mfma_f32_16x16x32_bf16 v[58:61], v[154:157], v[198:201], v[58:61]
	v_mfma_f32_16x16x32_bf16 v[58:61], v[168:171], v[202:205], v[58:61]
	v_mfma_f32_16x16x32_bf16 v[54:57], v[172:175], v[198:201], v[54:57]
	v_mfma_f32_16x16x32_bf16 v[54:57], v[180:183], v[202:205], v[54:57]
	v_mfma_f32_16x16x32_bf16 v[50:53], v[184:187], v[198:201], v[50:53]
	v_mfma_f32_16x16x32_bf16 v[50:53], v[188:191], v[202:205], v[50:53]
	v_mfma_f32_16x16x32_bf16 v[46:49], v[146:149], v[206:209], v[46:49]
	v_mfma_f32_16x16x32_bf16 v[46:49], v[150:153], v[210:213], v[46:49]
	v_mfma_f32_16x16x32_bf16 v[42:45], v[154:157], v[206:209], v[42:45]
	v_mfma_f32_16x16x32_bf16 v[42:45], v[168:171], v[210:213], v[42:45]
	v_mfma_f32_16x16x32_bf16 v[38:41], v[172:175], v[206:209], v[38:41]
	v_mfma_f32_16x16x32_bf16 v[38:41], v[180:183], v[210:213], v[38:41]
	v_mfma_f32_16x16x32_bf16 v[34:37], v[184:187], v[206:209], v[34:37]
	v_mfma_f32_16x16x32_bf16 v[34:37], v[188:191], v[210:213], v[34:37]
	s_setprio 0
	s_setprio 1
	v_mfma_f32_16x16x32_bf16 v[30:33], v[146:149], v[214:217], v[30:33]
	v_mfma_f32_16x16x32_bf16 v[30:33], v[150:153], v[218:221], v[30:33]
	v_mfma_f32_16x16x32_bf16 v[26:29], v[154:157], v[214:217], v[26:29]
	v_mfma_f32_16x16x32_bf16 v[26:29], v[168:171], v[218:221], v[26:29]
	v_mfma_f32_16x16x32_bf16 v[22:25], v[172:175], v[214:217], v[22:25]
	v_mfma_f32_16x16x32_bf16 v[22:25], v[180:183], v[218:221], v[22:25]
	v_mfma_f32_16x16x32_bf16 v[18:21], v[184:187], v[214:217], v[18:21]
	v_mfma_f32_16x16x32_bf16 v[18:21], v[188:191], v[218:221], v[18:21]
	v_mfma_f32_16x16x32_bf16 v[14:17], v[146:149], v[222:225], v[14:17]
	v_mfma_f32_16x16x32_bf16 v[14:17], v[150:153], v[226:229], v[14:17]
	v_mfma_f32_16x16x32_bf16 v[10:13], v[154:157], v[222:225], v[10:13]
	v_mfma_f32_16x16x32_bf16 v[10:13], v[168:171], v[226:229], v[10:13]
	v_mfma_f32_16x16x32_bf16 v[6:9], v[172:175], v[222:225], v[6:9]
	v_mfma_f32_16x16x32_bf16 v[6:9], v[180:183], v[226:229], v[6:9]
	v_mfma_f32_16x16x32_bf16 v[2:5], v[184:187], v[222:225], v[2:5]
	v_mfma_f32_16x16x32_bf16 v[2:5], v[188:191], v[226:229], v[2:5]
	s_setprio 0
	s_barrier
	s_add_i32 s59, 0, 0x18000
	v_add_u32_e32 v158, s59, v160
	s_add_i32 s64, 0, 0x1c000
	ds_read_b128 v[146:149], v158
	ds_read_b128 v[150:153], v158 offset:1024
	ds_read_b128 v[154:157], v158 offset:2048
	ds_read_b128 v[168:171], v158 offset:3072
	v_add_u32_e32 v158, s64, v160
	ds_read_b128 v[172:175], v158
	ds_read_b128 v[180:183], v158 offset:1024
	ds_read_b128 v[184:187], v158 offset:2048
	ds_read_b128 v[188:191], v158 offset:3072
	v_lshl_add_u64 v[158:159], s[78:79], 0, v[130:131]
	s_mov_b32 m0, s15
	s_nop 0
	global_load_lds_dwordx4 v[158:159], off
	v_lshl_add_u64 v[158:159], s[78:79], 0, v[134:135]
	s_mov_b32 m0, s27
	s_nop 0
	global_load_lds_dwordx4 v[158:159], off
	s_add_u32 s62, s78, 0x4000
	s_addc_u32 s63, s79, 0
	s_mov_b32 m0, s28
	v_lshl_add_u64 v[158:159], s[62:63], 0, v[130:131]
	ds_read_b128 v[198:201], v164 offset:32768
	ds_read_b128 v[202:205], v164 offset:33792
	ds_read_b128 v[206:209], v164 offset:34816
	ds_read_b128 v[210:213], v164 offset:35840
	ds_read_b128 v[214:217], v164 offset:36864
	ds_read_b128 v[218:221], v164 offset:37888
	ds_read_b128 v[222:225], v164 offset:38912
	ds_read_b128 v[226:229], v164 offset:39936
	global_load_lds_dwordx4 v[158:159], off
	v_lshl_add_u64 v[158:159], s[62:63], 0, v[134:135]
	s_mov_b32 m0, s29
	s_nop 0
	global_load_lds_dwordx4 v[158:159], off
	s_waitcnt vmcnt(8)
	s_waitcnt lgkmcnt(0)
	s_barrier
; #define PG8_STAGE(bufoff, gbase, voff) do { _Pragma("unroll") for (int _i = 0; _i < 2; ++_i) \
;         __builtin_amdgcn_global_load_lds((const unsigned*)((const char*)(gbase) + (voff)[_i]), (PG8_LAS unsigned*)(lds + (bufoff) + ldsw + _i * 8192), 16, 0, 0); } while (0)
; #define PG8_LDA(dst, b, h) do { _Pragma("unroll") for (int m = 0; m < 4; ++m) _Pragma("unroll") for (int k = 0; k < 2; ++k) dst[m][k] = *(const PG8_LAS bf16x8*)(lds + PG8_SA(b, h) + aoff + m * 2048 + k * 1024); } while (0)
; #define PG8_MMA(ai, bj, At, Bt) do { __builtin_amdgcn_s_setprio(1); _Pragma("unroll") for (int m = 0; m < 4; ++m) _Pragma("unroll") for (int n = 0; n < 2; ++n) _Pragma("unroll") for (int k = 0; k < 2; ++k) \
;         acc[ai][bj][m][n] = __builtin_amdgcn_mfma_f32_16x16x32_bf16(Bt[n][k], At[m][k], acc[ai][bj][m][n], 0, 0, 0); __builtin_amdgcn_s_setprio(0); } while (0)
; #define PG8_WAIT_V(n) asm volatile("s_waitcnt vmcnt(" #n ")" ::: "memory")
; #define PG8_WAIT_L(n) asm volatile("s_waitcnt lgkmcnt(" #n ")" ::: "memory")
; #define PG8_BAR __builtin_amdgcn_s_barrier()
; #define PG8_SCHED __builtin_amdgcn_sched_barrier(0)
; template <class Epi, class Sched, bool ALIGN_EPI = false, bool SP2 = false>
; __device__ __forceinline__ void gemm_phase(PG8_LAS unsigned char* lds, const Gemm g, const Sched& S, const Epi& E) {
;     ...
;             PG8_WAIT_V(8); PG8_WAIT_L(0); PG8_BAR; PG8_MMA(0, 0, At, B0); PG8_MMA(0, 1, At, B1); PG8_BAR; PG8_SCHED;
;             PG8_LDA(At, 1, 1); PG8_STAGE(PG8_SB(1, 0), b3, voffB); PG8_STAGE(PG8_SB(1, 1), b3 + hstep, voffB); PG8_STAGE(PG8_SA(1, 0), a3, voffA);
;             PG8_WAIT_V(8); PG8_WAIT_L(0); PG8_BAR; PG8_MMA(1, 0, At, B0); PG8_MMA(1, 1, At, B1); PG8_BAR; PG8_SCHED;
;     ...
;         }
;         if constexpr (Epi::HAS_MID) { if (seg == 0) E.mid(acc, cur, wr, wc, fr, fq); }
;         }
;         if constexpr (ALIGN_EPI) { if (wr == 0) PG8_BAR; }
	s_setprio 1
	s_waitcnt lgkmcnt(0)
	v_mfma_f32_16x16x32_bf16 v[126:129], v[146:149], v[198:201], v[126:129]
	v_mfma_f32_16x16x32_bf16 v[126:129], v[150:153], v[202:205], v[126:129]
	v_mfma_f32_16x16x32_bf16 v[122:125], v[154:157], v[198:201], v[122:125]
	v_mfma_f32_16x16x32_bf16 v[122:125], v[168:171], v[202:205], v[122:125]
	v_mfma_f32_16x16x32_bf16 v[118:121], v[172:175], v[198:201], v[118:121]
	v_mfma_f32_16x16x32_bf16 v[118:121], v[180:183], v[202:205], v[118:121]
	v_mfma_f32_16x16x32_bf16 v[114:117], v[184:187], v[198:201], v[114:117]
	v_mfma_f32_16x16x32_bf16 v[114:117], v[188:191], v[202:205], v[114:117]
	v_mfma_f32_16x16x32_bf16 v[110:113], v[146:149], v[206:209], v[110:113]
	v_mfma_f32_16x16x32_bf16 v[110:113], v[150:153], v[210:213], v[110:113]
	v_mfma_f32_16x16x32_bf16 v[106:109], v[154:157], v[206:209], v[106:109]
	v_mfma_f32_16x16x32_bf16 v[106:109], v[168:171], v[210:213], v[106:109]
	v_mfma_f32_16x16x32_bf16 v[102:105], v[172:175], v[206:209], v[102:105]
	v_mfma_f32_16x16x32_bf16 v[102:105], v[180:183], v[210:213], v[102:105]
	v_mfma_f32_16x16x32_bf16 v[98:101], v[184:187], v[206:209], v[98:101]
	v_mfma_f32_16x16x32_bf16 v[98:101], v[188:191], v[210:213], v[98:101]
	s_setprio 0
	s_setprio 1
	v_mfma_f32_16x16x32_bf16 v[94:97], v[146:149], v[214:217], v[94:97]
	v_mfma_f32_16x16x32_bf16 v[94:97], v[150:153], v[218:221], v[94:97]
	v_mfma_f32_16x16x32_bf16 v[90:93], v[154:157], v[214:217], v[90:93]
	v_mfma_f32_16x16x32_bf16 v[90:93], v[168:171], v[218:221], v[90:93]
	v_mfma_f32_16x16x32_bf16 v[86:89], v[172:175], v[214:217], v[86:89]
	v_mfma_f32_16x16x32_bf16 v[86:89], v[180:183], v[218:221], v[86:89]
	v_mfma_f32_16x16x32_bf16 v[82:85], v[184:187], v[214:217], v[82:85]
	v_mfma_f32_16x16x32_bf16 v[82:85], v[188:191], v[218:221], v[82:85]
	v_mfma_f32_16x16x32_bf16 v[78:81], v[146:149], v[222:225], v[78:81]
	v_mfma_f32_16x16x32_bf16 v[78:81], v[150:153], v[226:229], v[78:81]
	v_mfma_f32_16x16x32_bf16 v[74:77], v[154:157], v[222:225], v[74:77]
	v_mfma_f32_16x16x32_bf16 v[74:77], v[168:171], v[226:229], v[74:77]
	v_mfma_f32_16x16x32_bf16 v[70:73], v[172:175], v[222:225], v[70:73]
	v_mfma_f32_16x16x32_bf16 v[70:73], v[180:183], v[226:229], v[70:73]
	v_mfma_f32_16x16x32_bf16 v[66:69], v[184:187], v[222:225], v[66:69]
	v_mfma_f32_16x16x32_bf16 v[66:69], v[188:191], v[226:229], v[66:69]
	s_setprio 0
	s_barrier
	s_add_u32 s62, s76, 0x8000
	s_addc_u32 s63, s77, 0
	s_add_i32 s59, s59, s3
	v_lshl_add_u64 v[158:159], s[62:63], 0, v[132:133]
	s_mov_b32 m0, s59
	ds_read_b128 v[198:201], v164 offset:49152
	ds_read_b128 v[202:205], v164 offset:50176
	ds_read_b128 v[206:209], v164 offset:51200
	ds_read_b128 v[210:213], v164 offset:52224
	ds_read_b128 v[214:217], v164 offset:53248
	ds_read_b128 v[218:221], v164 offset:54272
	ds_read_b128 v[222:225], v164 offset:55296
	ds_read_b128 v[226:229], v164 offset:56320
	global_load_lds_dwordx4 v[158:159], off
	s_add_i32 m0, s59, 0x2000
	v_lshl_add_u64 v[158:159], s[62:63], 0, v[136:137]
	s_add_u32 s62, s76, 0xc000
	s_addc_u32 s63, s77, 0
	s_add_i32 s59, s64, s3
	global_load_lds_dwordx4 v[158:159], off
	v_lshl_add_u64 v[158:159], s[62:63], 0, v[132:133]
	s_mov_b32 m0, s59
	s_nop 0
	global_load_lds_dwordx4 v[158:159], off
	v_lshl_add_u64 v[158:159], s[62:63], 0, v[136:137]
	s_add_i32 m0, s59, 0x2000
	s_nop 0
	global_load_lds_dwordx4 v[158:159], off
	s_waitcnt vmcnt(6)
	s_waitcnt lgkmcnt(0)
	s_barrier
	s_setprio 1
	s_waitcnt lgkmcnt(0)
	v_mfma_f32_16x16x32_bf16 v[62:65], v[146:149], v[198:201], v[62:65]
	v_mfma_f32_16x16x32_bf16 v[62:65], v[150:153], v[202:205], v[62:65]
	v_mfma_f32_16x16x32_bf16 v[58:61], v[154:157], v[198:201], v[58:61]
	v_mfma_f32_16x16x32_bf16 v[58:61], v[168:171], v[202:205], v[58:61]
	v_mfma_f32_16x16x32_bf16 v[54:57], v[172:175], v[198:201], v[54:57]
	v_mfma_f32_16x16x32_bf16 v[54:57], v[180:183], v[202:205], v[54:57]
	v_mfma_f32_16x16x32_bf16 v[50:53], v[184:187], v[198:201], v[50:53]
	v_mfma_f32_16x16x32_bf16 v[50:53], v[188:191], v[202:205], v[50:53]
	v_mfma_f32_16x16x32_bf16 v[46:49], v[146:149], v[206:209], v[46:49]
	v_mfma_f32_16x16x32_bf16 v[46:49], v[150:153], v[210:213], v[46:49]
	v_mfma_f32_16x16x32_bf16 v[42:45], v[154:157], v[206:209], v[42:45]
	v_mfma_f32_16x16x32_bf16 v[42:45], v[168:171], v[210:213], v[42:45]
	v_mfma_f32_16x16x32_bf16 v[38:41], v[172:175], v[206:209], v[38:41]
	v_mfma_f32_16x16x32_bf16 v[38:41], v[180:183], v[210:213], v[38:41]
	v_mfma_f32_16x16x32_bf16 v[34:37], v[184:187], v[206:209], v[34:37]
	v_mfma_f32_16x16x32_bf16 v[34:37], v[188:191], v[210:213], v[34:37]
	s_setprio 0
	s_setprio 1
	v_mfma_f32_16x16x32_bf16 v[30:33], v[146:149], v[214:217], v[30:33]
	v_mfma_f32_16x16x32_bf16 v[30:33], v[150:153], v[218:221], v[30:33]
	v_mfma_f32_16x16x32_bf16 v[26:29], v[154:157], v[214:217], v[26:29]
	v_mfma_f32_16x16x32_bf16 v[26:29], v[168:171], v[218:221], v[26:29]
	v_mfma_f32_16x16x32_bf16 v[22:25], v[172:175], v[214:217], v[22:25]
	v_mfma_f32_16x16x32_bf16 v[22:25], v[180:183], v[218:221], v[22:25]
	v_mfma_f32_16x16x32_bf16 v[18:21], v[184:187], v[214:217], v[18:21]
	v_mfma_f32_16x16x32_bf16 v[18:21], v[188:191], v[218:221], v[18:21]
	v_mfma_f32_16x16x32_bf16 v[14:17], v[146:149], v[222:225], v[14:17]
	v_mfma_f32_16x16x32_bf16 v[14:17], v[150:153], v[226:229], v[14:17]
	v_mfma_f32_16x16x32_bf16 v[10:13], v[154:157], v[222:225], v[10:13]
	v_mfma_f32_16x16x32_bf16 v[10:13], v[168:171], v[226:229], v[10:13]
	v_mfma_f32_16x16x32_bf16 v[6:9], v[172:175], v[222:225], v[6:9]
	v_mfma_f32_16x16x32_bf16 v[6:9], v[180:183], v[226:229], v[6:9]
	v_mfma_f32_16x16x32_bf16 v[2:5], v[184:187], v[222:225], v[2:5]
	v_mfma_f32_16x16x32_bf16 v[2:5], v[188:191], v[226:229], v[2:5]
	s_setprio 0
	s_barrier
	s_add_i32 s58, s58, 2
	s_add_u32 s72, s72, 0x10000
	s_addc_u32 s73, s73, 0
	s_add_u32 s33, s33, 0x10000
	s_addc_u32 s56, s56, 0
	s_cmp_gt_u32 s58, 61
	s_cbranch_scc0 .LBB0_290
	s_and_b64 vcc, exec, s[12:13]
	s_cbranch_vccz .LBB0_293
	s_barrier

; #define PG8_STAGE(bufoff, gbase, voff) do { _Pragma("unroll") for (int _i = 0; _i < 2; ++_i) \
;         __builtin_amdgcn_global_load_lds((const unsigned*)((const char*)(gbase) + (voff)[_i]), (PG8_LAS unsigned*)(lds + (bufoff) + ldsw + _i * 8192), 16, 0, 0); } while (0)
; #define PG8_LDA(dst, b, h) do { _Pragma("unroll") for (int m = 0; m < 4; ++m) _Pragma("unroll") for (int k = 0; k < 2; ++k) dst[m][k] = *(const PG8_LAS bf16x8*)(lds + PG8_SA(b, h) + aoff + m * 2048 + k * 1024); } while (0)
; #define PG8_LDB(dst, b, h) do { _Pragma("unroll") for (int n = 0; n < 2; ++n) _Pragma("unroll") for (int k = 0; k < 2; ++k) dst[n][k] = *(const PG8_LAS bf16x8*)(lds + PG8_SB(b, h) + boff + n * 2048 + k * 1024); } while (0)
; #define PG8_MMA(ai, bj, At, Bt) do { __builtin_amdgcn_s_setprio(1); _Pragma("unroll") for (int m = 0; m < 4; ++m) _Pragma("unroll") for (int n = 0; n < 2; ++n) _Pragma("unroll") for (int k = 0; k < 2; ++k) \
;         acc[ai][bj][m][n] = __builtin_amdgcn_mfma_f32_16x16x32_bf16(Bt[n][k], At[m][k], acc[ai][bj][m][n], 0, 0, 0); __builtin_amdgcn_s_setprio(0); } while (0)
; #define PG8_WAIT_V(n) asm volatile("s_waitcnt vmcnt(" #n ")" ::: "memory")
; #define PG8_WAIT_L(n) asm volatile("s_waitcnt lgkmcnt(" #n ")" ::: "memory")
; template <class Epi, class Sched, bool ALIGN_EPI = false, bool SP2 = false>
; __device__ __forceinline__ void gemm_phase(PG8_LAS unsigned char* lds, const Gemm g, const Sched& S, const Epi& E) {
;     ...
;         for (; t < tend; t += 2) {
;             const bool last = (t == nt - 2);
;             const char* a1 = cA + (size_t)(t + 1) * kstep;
;             const char* a2 = last ? nA : cA + (size_t)(t + 2) * kstep; const char* b2 = last ? nB : cB + (size_t)(t + 2) * kstep;
;             const char* a3 = a2 + kstep; const char* b3 = b2 + kstep;
;             if (last && has_next) S.a_ready(nxt);
;             if constexpr (SP2) {
;             PG8_LDB(B0, 0, 0); PG8_LDB(B1, 0, 1); PG8_SCHED; PG8_LDA(At, 0, 0); PG8_STAGE(PG8_SA(1, 1), a1 + hstep, voffA);
;             PG8_WAIT_V(8); PG8_WAIT_L(0); PG8_BAR; PG8_MMA(0, 0, At, B0); PG8_MMA(0, 1, At, B1); PG8_BAR; PG8_SCHED;
;             PG8_LDA(At, 0, 1); PG8_STAGE(PG8_SB(0, 0), b2, voffB); PG8_STAGE(PG8_SB(0, 1), b2 + hstep, voffB); PG8_STAGE(PG8_SA(0, 0), a2, voffA);
;             PG8_WAIT_V(8); PG8_WAIT_L(0); PG8_BAR; PG8_MMA(1, 0, At, B0); PG8_MMA(1, 1, At, B1); PG8_BAR; PG8_SCHED;
.LBB0_757:
	ds_read_b128 v[154:157], v149
	ds_read_b128 v[158:161], v149 offset:1024
	ds_read_b128 v[162:165], v149 offset:2048
	ds_read_b128 v[166:169], v149 offset:3072
	ds_read_b128 v[170:173], v150
	ds_read_b128 v[174:177], v150 offset:1024
	ds_read_b128 v[180:183], v150 offset:2048
	ds_read_b128 v[184:187], v150 offset:3072
	s_add_u32 s46, s44, 0x4000
	s_addc_u32 s47, s45, 0
	s_cmp_eq_u32 s70, 60
	s_cselect_b32 s50, s39, s46
	s_cselect_b32 s51, s17, s47
	s_cselect_b32 s48, s41, s68
	s_cselect_b32 s49, s15, s69
	s_add_u32 s46, s50, 0x8000
	s_addc_u32 s47, s51, 0
	s_sub_u32 s46, s44, 0x4000
	s_subb_u32 s47, s45, 0
	v_lshl_add_u64 v[146:147], s[46:47], 0, v[130:131]
	s_mov_b32 m0, s57
	s_nop 0
	global_load_lds_dwordx4 v[146:147], off
	v_lshl_add_u64 v[146:147], s[46:47], 0, v[134:135]
	s_mov_b32 m0, s58
	s_nop 0
	global_load_lds_dwordx4 v[146:147], off
	v_lshl_add_u64 v[146:147], s[44:45], 0, v[138:139]
	s_add_i32 m0, s26, 0xc000
	ds_read_b128 v[188:191], v151
	ds_read_b128 v[198:201], v151 offset:1024
	ds_read_b128 v[202:205], v151 offset:2048
	ds_read_b128 v[206:209], v151 offset:3072
	ds_read_b128 v[210:213], v151 offset:4096
	ds_read_b128 v[214:217], v151 offset:5120
	ds_read_b128 v[218:221], v151 offset:6144
	ds_read_b128 v[222:225], v151 offset:7168
	global_load_lds_dwordx4 v[146:147], off
	v_lshl_add_u64 v[146:147], s[44:45], 0, v[140:141]
	s_add_i32 m0, s26, 0xe000
	s_nop 0
	global_load_lds_dwordx4 v[146:147], off
	s_waitcnt vmcnt(8)
	s_waitcnt lgkmcnt(0)
	s_barrier
	s_setprio 1
	s_waitcnt lgkmcnt(0)
	v_mfma_f32_16x16x32_bf16 v[126:129], v[154:157], v[188:191], v[126:129]
	v_mfma_f32_16x16x32_bf16 v[126:129], v[158:161], v[198:201], v[126:129]
	v_mfma_f32_16x16x32_bf16 v[122:125], v[162:165], v[188:191], v[122:125]
	v_mfma_f32_16x16x32_bf16 v[122:125], v[166:169], v[198:201], v[122:125]
	v_mfma_f32_16x16x32_bf16 v[118:121], v[170:173], v[188:191], v[118:121]
	v_mfma_f32_16x16x32_bf16 v[118:121], v[174:177], v[198:201], v[118:121]
	v_mfma_f32_16x16x32_bf16 v[114:117], v[180:183], v[188:191], v[114:117]
	v_mfma_f32_16x16x32_bf16 v[114:117], v[184:187], v[198:201], v[114:117]
	v_mfma_f32_16x16x32_bf16 v[110:113], v[154:157], v[202:205], v[110:113]
	v_mfma_f32_16x16x32_bf16 v[110:113], v[158:161], v[206:209], v[110:113]
	v_mfma_f32_16x16x32_bf16 v[106:109], v[162:165], v[202:205], v[106:109]
	v_mfma_f32_16x16x32_bf16 v[106:109], v[166:169], v[206:209], v[106:109]
	v_mfma_f32_16x16x32_bf16 v[102:105], v[170:173], v[202:205], v[102:105]
	v_mfma_f32_16x16x32_bf16 v[102:105], v[174:177], v[206:209], v[102:105]
	v_mfma_f32_16x16x32_bf16 v[98:101], v[180:183], v[202:205], v[98:101]
	v_mfma_f32_16x16x32_bf16 v[98:101], v[184:187], v[206:209], v[98:101]
	s_setprio 0
	s_setprio 1
	v_mfma_f32_16x16x32_bf16 v[94:97], v[154:157], v[210:213], v[94:97]
	v_mfma_f32_16x16x32_bf16 v[94:97], v[158:161], v[214:217], v[94:97]
	v_mfma_f32_16x16x32_bf16 v[90:93], v[162:165], v[210:213], v[90:93]
	v_mfma_f32_16x16x32_bf16 v[90:93], v[166:169], v[214:217], v[90:93]
	v_mfma_f32_16x16x32_bf16 v[86:89], v[170:173], v[210:213], v[86:89]
	v_mfma_f32_16x16x32_bf16 v[86:89], v[174:177], v[214:217], v[86:89]
	v_mfma_f32_16x16x32_bf16 v[82:85], v[180:183], v[210:213], v[82:85]
	v_mfma_f32_16x16x32_bf16 v[82:85], v[184:187], v[214:217], v[82:85]
	v_mfma_f32_16x16x32_bf16 v[78:81], v[154:157], v[218:221], v[78:81]
	v_mfma_f32_16x16x32_bf16 v[78:81], v[158:161], v[222:225], v[78:81]
	v_mfma_f32_16x16x32_bf16 v[74:77], v[162:165], v[218:221], v[74:77]
	v_mfma_f32_16x16x32_bf16 v[74:77], v[166:169], v[222:225], v[74:77]
	v_mfma_f32_16x16x32_bf16 v[70:73], v[170:173], v[218:221], v[70:73]
	v_mfma_f32_16x16x32_bf16 v[70:73], v[174:177], v[222:225], v[70:73]
	v_mfma_f32_16x16x32_bf16 v[66:69], v[180:183], v[218:221], v[66:69]
	v_mfma_f32_16x16x32_bf16 v[66:69], v[184:187], v[222:225], v[66:69]
	s_setprio 0
	s_barrier
	s_add_i32 s71, s59, s3
	v_lshl_add_u64 v[146:147], s[48:49], 0, v[132:133]
	s_mov_b32 m0, s71
	ds_read_b128 v[188:191], v151 offset:16384
	ds_read_b128 v[198:201], v151 offset:17408
	ds_read_b128 v[202:205], v151 offset:18432
	ds_read_b128 v[206:209], v151 offset:19456
	ds_read_b128 v[210:213], v151 offset:20480
	ds_read_b128 v[214:217], v151 offset:21504
	ds_read_b128 v[218:221], v151 offset:22528
	ds_read_b128 v[222:225], v151 offset:23552
	global_load_lds_dwordx4 v[146:147], off
	s_add_i32 m0, s71, 0x2000
	s_add_u32 s72, s48, 0x4000
	v_lshl_add_u64 v[146:147], s[48:49], 0, v[136:137]
	s_addc_u32 s73, s49, 0
	s_add_i32 s71, s61, s3
	global_load_lds_dwordx4 v[146:147], off
	v_lshl_add_u64 v[146:147], s[72:73], 0, v[132:133]
	s_mov_b32 m0, s71
	s_nop 0
	global_load_lds_dwordx4 v[146:147], off
	v_lshl_add_u64 v[146:147], s[72:73], 0, v[136:137]
	s_add_i32 m0, s71, 0x2000
	s_nop 0
	global_load_lds_dwordx4 v[146:147], off
	s_waitcnt vmcnt(6)
	s_waitcnt lgkmcnt(0)
	s_barrier
; #define PG8_STAGE(bufoff, gbase, voff) do { _Pragma("unroll") for (int _i = 0; _i < 2; ++_i) \
;         __builtin_amdgcn_global_load_lds((const unsigned*)((const char*)(gbase) + (voff)[_i]), (PG8_LAS unsigned*)(lds + (bufoff) + ldsw + _i * 8192), 16, 0, 0); } while (0)
; #define PG8_LDA(dst, b, h) do { _Pragma("unroll") for (int m = 0; m < 4; ++m) _Pragma("unroll") for (int k = 0; k < 2; ++k) dst[m][k] = *(const PG8_LAS bf16x8*)(lds + PG8_SA(b, h) + aoff + m * 2048 + k * 1024); } while (0)
; #define PG8_LDB(dst, b, h) do { _Pragma("unroll") for (int n = 0; n < 2; ++n) _Pragma("unroll") for (int k = 0; k < 2; ++k) dst[n][k] = *(const PG8_LAS bf16x8*)(lds + PG8_SB(b, h) + boff + n * 2048 + k * 1024); } while (0)
; #define PG8_MMA(ai, bj, At, Bt) do { __builtin_amdgcn_s_setprio(1); _Pragma("unroll") for (int m = 0; m < 4; ++m) _Pragma("unroll") for (int n = 0; n < 2; ++n) _Pragma("unroll") for (int k = 0; k < 2; ++k) \
;         acc[ai][bj][m][n] = __builtin_amdgcn_mfma_f32_16x16x32_bf16(Bt[n][k], At[m][k], acc[ai][bj][m][n], 0, 0, 0); __builtin_amdgcn_s_setprio(0); } while (0)
; #define PG8_WAIT_V(n) asm volatile("s_waitcnt vmcnt(" #n ")" ::: "memory")
; #define PG8_WAIT_L(n) asm volatile("s_waitcnt lgkmcnt(" #n ")" ::: "memory")
; #define PG8_BAR __builtin_amdgcn_s_barrier()
; #define PG8_SCHED __builtin_amdgcn_sched_barrier(0)
; template <class Epi, class Sched, bool ALIGN_EPI = false, bool SP2 = false>
; __device__ __forceinline__ void gemm_phase(PG8_LAS unsigned char* lds, const Gemm g, const Sched& S, const Epi& E) {
;     ...
;             PG8_WAIT_V(8); PG8_WAIT_L(0); PG8_BAR; PG8_MMA(1, 0, At, B0); PG8_MMA(1, 1, At, B1); PG8_BAR; PG8_SCHED;
;             PG8_LDB(B0, 1, 0); PG8_LDB(B1, 1, 1); PG8_SCHED; PG8_LDA(At, 1, 0); PG8_STAGE(PG8_SA(0, 1), a2 + hstep, voffA);
;             PG8_WAIT_V(8); PG8_WAIT_L(0); PG8_BAR; PG8_MMA(0, 0, At, B0); PG8_MMA(0, 1, At, B1); PG8_BAR; PG8_SCHED;
	s_setprio 1
	s_waitcnt lgkmcnt(0)
	v_mfma_f32_16x16x32_bf16 v[62:65], v[154:157], v[188:191], v[62:65]
	v_mfma_f32_16x16x32_bf16 v[62:65], v[158:161], v[198:201], v[62:65]
	v_mfma_f32_16x16x32_bf16 v[58:61], v[162:165], v[188:191], v[58:61]
	v_mfma_f32_16x16x32_bf16 v[58:61], v[166:169], v[198:201], v[58:61]
	v_mfma_f32_16x16x32_bf16 v[54:57], v[170:173], v[188:191], v[54:57]
	v_mfma_f32_16x16x32_bf16 v[54:57], v[174:177], v[198:201], v[54:57]
	v_mfma_f32_16x16x32_bf16 v[50:53], v[180:183], v[188:191], v[50:53]
	v_mfma_f32_16x16x32_bf16 v[50:53], v[184:187], v[198:201], v[50:53]
	v_mfma_f32_16x16x32_bf16 v[46:49], v[154:157], v[202:205], v[46:49]
	v_mfma_f32_16x16x32_bf16 v[46:49], v[158:161], v[206:209], v[46:49]
	v_mfma_f32_16x16x32_bf16 v[42:45], v[162:165], v[202:205], v[42:45]
	v_mfma_f32_16x16x32_bf16 v[42:45], v[166:169], v[206:209], v[42:45]
	v_mfma_f32_16x16x32_bf16 v[38:41], v[170:173], v[202:205], v[38:41]
	v_mfma_f32_16x16x32_bf16 v[38:41], v[174:177], v[206:209], v[38:41]
	v_mfma_f32_16x16x32_bf16 v[34:37], v[180:183], v[202:205], v[34:37]
	v_mfma_f32_16x16x32_bf16 v[34:37], v[184:187], v[206:209], v[34:37]
	s_setprio 0
	s_setprio 1
	v_mfma_f32_16x16x32_bf16 v[30:33], v[154:157], v[210:213], v[30:33]
	v_mfma_f32_16x16x32_bf16 v[30:33], v[158:161], v[214:217], v[30:33]
	v_mfma_f32_16x16x32_bf16 v[26:29], v[162:165], v[210:213], v[26:29]
	v_mfma_f32_16x16x32_bf16 v[26:29], v[166:169], v[214:217], v[26:29]
	v_mfma_f32_16x16x32_bf16 v[22:25], v[170:173], v[210:213], v[22:25]
	v_mfma_f32_16x16x32_bf16 v[22:25], v[174:177], v[214:217], v[22:25]
	v_mfma_f32_16x16x32_bf16 v[18:21], v[180:183], v[210:213], v[18:21]
	v_mfma_f32_16x16x32_bf16 v[18:21], v[184:187], v[214:217], v[18:21]
	v_mfma_f32_16x16x32_bf16 v[14:17], v[154:157], v[218:221], v[14:17]
	v_mfma_f32_16x16x32_bf16 v[14:17], v[158:161], v[222:225], v[14:17]
	v_mfma_f32_16x16x32_bf16 v[10:13], v[162:165], v[218:221], v[10:13]
	v_mfma_f32_16x16x32_bf16 v[10:13], v[166:169], v[222:225], v[10:13]
	v_mfma_f32_16x16x32_bf16 v[6:9], v[170:173], v[218:221], v[6:9]
	v_mfma_f32_16x16x32_bf16 v[6:9], v[174:177], v[222:225], v[6:9]
	v_mfma_f32_16x16x32_bf16 v[2:5], v[180:183], v[218:221], v[2:5]
	v_mfma_f32_16x16x32_bf16 v[2:5], v[184:187], v[222:225], v[2:5]
	s_setprio 0
	s_barrier
	s_add_i32 s71, 0, 0x18000
	v_add_u32_e32 v146, s71, v1
	s_add_i32 s72, 0, 0x1c000
	ds_read_b128 v[154:157], v146
	ds_read_b128 v[158:161], v146 offset:1024
	ds_read_b128 v[162:165], v146 offset:2048
	ds_read_b128 v[166:169], v146 offset:3072
	v_add_u32_e32 v146, s72, v1
	ds_read_b128 v[170:173], v146
	ds_read_b128 v[174:177], v146 offset:1024
	ds_read_b128 v[180:183], v146 offset:2048
	ds_read_b128 v[184:187], v146 offset:3072
	v_lshl_add_u64 v[146:147], s[50:51], 0, v[130:131]
	s_mov_b32 m0, s26
	s_nop 0
	global_load_lds_dwordx4 v[146:147], off
	v_lshl_add_u64 v[146:147], s[50:51], 0, v[134:135]
	s_mov_b32 m0, s27
	s_nop 0
	global_load_lds_dwordx4 v[146:147], off
	s_add_u32 s50, s50, 0x4000
	s_addc_u32 s51, s51, 0
	s_mov_b32 m0, s28
	v_lshl_add_u64 v[146:147], s[50:51], 0, v[130:131]
	ds_read_b128 v[188:191], v151 offset:32768
	ds_read_b128 v[198:201], v151 offset:33792
	ds_read_b128 v[202:205], v151 offset:34816
	ds_read_b128 v[206:209], v151 offset:35840
	ds_read_b128 v[210:213], v151 offset:36864
	ds_read_b128 v[214:217], v151 offset:37888
	ds_read_b128 v[218:221], v151 offset:38912
	ds_read_b128 v[222:225], v151 offset:39936
	global_load_lds_dwordx4 v[146:147], off
	v_lshl_add_u64 v[146:147], s[50:51], 0, v[134:135]
	s_mov_b32 m0, s29
	s_nop 0
	global_load_lds_dwordx4 v[146:147], off
	s_waitcnt vmcnt(8)
	s_waitcnt lgkmcnt(0)
	s_barrier
; #define PG8_STAGE(bufoff, gbase, voff) do { _Pragma("unroll") for (int _i = 0; _i < 2; ++_i) \
;         __builtin_amdgcn_global_load_lds((const unsigned*)((const char*)(gbase) + (voff)[_i]), (PG8_LAS unsigned*)(lds + (bufoff) + ldsw + _i * 8192), 16, 0, 0); } while (0)
; #define PG8_LDA(dst, b, h) do { _Pragma("unroll") for (int m = 0; m < 4; ++m) _Pragma("unroll") for (int k = 0; k < 2; ++k) dst[m][k] = *(const PG8_LAS bf16x8*)(lds + PG8_SA(b, h) + aoff + m * 2048 + k * 1024); } while (0)
; #define PG8_MMA(ai, bj, At, Bt) do { __builtin_amdgcn_s_setprio(1); _Pragma("unroll") for (int m = 0; m < 4; ++m) _Pragma("unroll") for (int n = 0; n < 2; ++n) _Pragma("unroll") for (int k = 0; k < 2; ++k) \
;         acc[ai][bj][m][n] = __builtin_amdgcn_mfma_f32_16x16x32_bf16(Bt[n][k], At[m][k], acc[ai][bj][m][n], 0, 0, 0); __builtin_amdgcn_s_setprio(0); } while (0)
; #define PG8_WAIT_V(n) asm volatile("s_waitcnt vmcnt(" #n ")" ::: "memory")
; #define PG8_WAIT_L(n) asm volatile("s_waitcnt lgkmcnt(" #n ")" ::: "memory")
; #define PG8_BAR __builtin_amdgcn_s_barrier()
; #define PG8_SCHED __builtin_amdgcn_sched_barrier(0)
; template <class Epi, class Sched, bool ALIGN_EPI = false, bool SP2 = false>
; __device__ __forceinline__ void gemm_phase(PG8_LAS unsigned char* lds, const Gemm g, const Sched& S, const Epi& E) {
;     ...
;             PG8_WAIT_V(8); PG8_WAIT_L(0); PG8_BAR; PG8_MMA(0, 0, At, B0); PG8_MMA(0, 1, At, B1); PG8_BAR; PG8_SCHED;
;             PG8_LDA(At, 1, 1); PG8_STAGE(PG8_SB(1, 0), b3, voffB); PG8_STAGE(PG8_SB(1, 1), b3 + hstep, voffB); PG8_STAGE(PG8_SA(1, 0), a3, voffA);
;             PG8_WAIT_V(8); PG8_WAIT_L(0); PG8_BAR; PG8_MMA(1, 0, At, B0); PG8_MMA(1, 1, At, B1); PG8_BAR; PG8_SCHED;
;     ...
;         }
;         if constexpr (Epi::HAS_MID) { if (seg == 0) E.mid(acc, cur, wr, wc, fr, fq); }
;         }
;         if constexpr (ALIGN_EPI) { if (wr == 0) PG8_BAR; }
	s_setprio 1
	s_waitcnt lgkmcnt(0)
	v_mfma_f32_16x16x32_bf16 v[126:129], v[154:157], v[188:191], v[126:129]
	v_mfma_f32_16x16x32_bf16 v[126:129], v[158:161], v[198:201], v[126:129]
	v_mfma_f32_16x16x32_bf16 v[122:125], v[162:165], v[188:191], v[122:125]
	v_mfma_f32_16x16x32_bf16 v[122:125], v[166:169], v[198:201], v[122:125]
	v_mfma_f32_16x16x32_bf16 v[118:121], v[170:173], v[188:191], v[118:121]
	v_mfma_f32_16x16x32_bf16 v[118:121], v[174:177], v[198:201], v[118:121]
	v_mfma_f32_16x16x32_bf16 v[114:117], v[180:183], v[188:191], v[114:117]
	v_mfma_f32_16x16x32_bf16 v[114:117], v[184:187], v[198:201], v[114:117]
	v_mfma_f32_16x16x32_bf16 v[110:113], v[154:157], v[202:205], v[110:113]
	v_mfma_f32_16x16x32_bf16 v[110:113], v[158:161], v[206:209], v[110:113]
	v_mfma_f32_16x16x32_bf16 v[106:109], v[162:165], v[202:205], v[106:109]
	v_mfma_f32_16x16x32_bf16 v[106:109], v[166:169], v[206:209], v[106:109]
	v_mfma_f32_16x16x32_bf16 v[102:105], v[170:173], v[202:205], v[102:105]
	v_mfma_f32_16x16x32_bf16 v[102:105], v[174:177], v[206:209], v[102:105]
	v_mfma_f32_16x16x32_bf16 v[98:101], v[180:183], v[202:205], v[98:101]
	v_mfma_f32_16x16x32_bf16 v[98:101], v[184:187], v[206:209], v[98:101]
	s_setprio 0
	s_setprio 1
	v_mfma_f32_16x16x32_bf16 v[94:97], v[154:157], v[210:213], v[94:97]
	v_mfma_f32_16x16x32_bf16 v[94:97], v[158:161], v[214:217], v[94:97]
	v_mfma_f32_16x16x32_bf16 v[90:93], v[162:165], v[210:213], v[90:93]
	v_mfma_f32_16x16x32_bf16 v[90:93], v[166:169], v[214:217], v[90:93]
	v_mfma_f32_16x16x32_bf16 v[86:89], v[170:173], v[210:213], v[86:89]
	v_mfma_f32_16x16x32_bf16 v[86:89], v[174:177], v[214:217], v[86:89]
	v_mfma_f32_16x16x32_bf16 v[82:85], v[180:183], v[210:213], v[82:85]
	v_mfma_f32_16x16x32_bf16 v[82:85], v[184:187], v[214:217], v[82:85]
	v_mfma_f32_16x16x32_bf16 v[78:81], v[154:157], v[218:221], v[78:81]
	v_mfma_f32_16x16x32_bf16 v[78:81], v[158:161], v[222:225], v[78:81]
	v_mfma_f32_16x16x32_bf16 v[74:77], v[162:165], v[218:221], v[74:77]
	v_mfma_f32_16x16x32_bf16 v[74:77], v[166:169], v[222:225], v[74:77]
	v_mfma_f32_16x16x32_bf16 v[70:73], v[170:173], v[218:221], v[70:73]
	v_mfma_f32_16x16x32_bf16 v[70:73], v[174:177], v[222:225], v[70:73]
	v_mfma_f32_16x16x32_bf16 v[66:69], v[180:183], v[218:221], v[66:69]
	v_mfma_f32_16x16x32_bf16 v[66:69], v[184:187], v[222:225], v[66:69]
	s_setprio 0
	s_barrier
	s_add_u32 s50, s48, 0x8000
	s_addc_u32 s51, s49, 0
	s_add_i32 s71, s71, s3
	v_lshl_add_u64 v[146:147], s[50:51], 0, v[132:133]
	s_mov_b32 m0, s71
	ds_read_b128 v[188:191], v151 offset:49152
	ds_read_b128 v[198:201], v151 offset:50176
	ds_read_b128 v[202:205], v151 offset:51200
	ds_read_b128 v[206:209], v151 offset:52224
	ds_read_b128 v[210:213], v151 offset:53248
	ds_read_b128 v[214:217], v151 offset:54272
	ds_read_b128 v[218:221], v151 offset:55296
	ds_read_b128 v[222:225], v151 offset:56320
	global_load_lds_dwordx4 v[146:147], off
	s_add_i32 m0, s71, 0x2000
	s_add_u32 s48, s48, 0xc000
	v_lshl_add_u64 v[146:147], s[50:51], 0, v[136:137]
	s_addc_u32 s49, s49, 0
	s_add_i32 s50, s72, s3
	global_load_lds_dwordx4 v[146:147], off
	v_lshl_add_u64 v[146:147], s[48:49], 0, v[132:133]
	s_mov_b32 m0, s50
	s_nop 0
	global_load_lds_dwordx4 v[146:147], off
	v_lshl_add_u64 v[146:147], s[48:49], 0, v[136:137]
	s_add_i32 m0, s50, 0x2000
	s_nop 0
	global_load_lds_dwordx4 v[146:147], off
	s_waitcnt vmcnt(6)
	s_waitcnt lgkmcnt(0)
	s_barrier
	s_setprio 1
	s_waitcnt lgkmcnt(0)
	v_mfma_f32_16x16x32_bf16 v[62:65], v[154:157], v[188:191], v[62:65]
	v_mfma_f32_16x16x32_bf16 v[62:65], v[158:161], v[198:201], v[62:65]
	v_mfma_f32_16x16x32_bf16 v[58:61], v[162:165], v[188:191], v[58:61]
	v_mfma_f32_16x16x32_bf16 v[58:61], v[166:169], v[198:201], v[58:61]
	v_mfma_f32_16x16x32_bf16 v[54:57], v[170:173], v[188:191], v[54:57]
	v_mfma_f32_16x16x32_bf16 v[54:57], v[174:177], v[198:201], v[54:57]
	v_mfma_f32_16x16x32_bf16 v[50:53], v[180:183], v[188:191], v[50:53]
	v_mfma_f32_16x16x32_bf16 v[50:53], v[184:187], v[198:201], v[50:53]
	v_mfma_f32_16x16x32_bf16 v[46:49], v[154:157], v[202:205], v[46:49]
	v_mfma_f32_16x16x32_bf16 v[46:49], v[158:161], v[206:209], v[46:49]
	v_mfma_f32_16x16x32_bf16 v[42:45], v[162:165], v[202:205], v[42:45]
	v_mfma_f32_16x16x32_bf16 v[42:45], v[166:169], v[206:209], v[42:45]
	v_mfma_f32_16x16x32_bf16 v[38:41], v[170:173], v[202:205], v[38:41]
	v_mfma_f32_16x16x32_bf16 v[38:41], v[174:177], v[206:209], v[38:41]
	v_mfma_f32_16x16x32_bf16 v[34:37], v[180:183], v[202:205], v[34:37]
	v_mfma_f32_16x16x32_bf16 v[34:37], v[184:187], v[206:209], v[34:37]
	s_setprio 0
	s_setprio 1
	v_mfma_f32_16x16x32_bf16 v[30:33], v[154:157], v[210:213], v[30:33]
	v_mfma_f32_16x16x32_bf16 v[30:33], v[158:161], v[214:217], v[30:33]
	v_mfma_f32_16x16x32_bf16 v[26:29], v[162:165], v[210:213], v[26:29]
	v_mfma_f32_16x16x32_bf16 v[26:29], v[166:169], v[214:217], v[26:29]
	v_mfma_f32_16x16x32_bf16 v[22:25], v[170:173], v[210:213], v[22:25]
	v_mfma_f32_16x16x32_bf16 v[22:25], v[174:177], v[214:217], v[22:25]
	v_mfma_f32_16x16x32_bf16 v[18:21], v[180:183], v[210:213], v[18:21]
	v_mfma_f32_16x16x32_bf16 v[18:21], v[184:187], v[214:217], v[18:21]
	v_mfma_f32_16x16x32_bf16 v[14:17], v[154:157], v[218:221], v[14:17]
	v_mfma_f32_16x16x32_bf16 v[14:17], v[158:161], v[222:225], v[14:17]
	v_mfma_f32_16x16x32_bf16 v[10:13], v[162:165], v[218:221], v[10:13]
	v_mfma_f32_16x16x32_bf16 v[10:13], v[166:169], v[222:225], v[10:13]
	v_mfma_f32_16x16x32_bf16 v[6:9], v[170:173], v[218:221], v[6:9]
	v_mfma_f32_16x16x32_bf16 v[6:9], v[174:177], v[222:225], v[6:9]
	v_mfma_f32_16x16x32_bf16 v[2:5], v[180:183], v[218:221], v[2:5]
	v_mfma_f32_16x16x32_bf16 v[2:5], v[184:187], v[222:225], v[2:5]
	s_setprio 0
	s_barrier
	s_add_i32 s70, s70, 2
	s_add_u32 s44, s44, 0x10000
	s_addc_u32 s45, s45, 0
	s_add_u32 s68, s68, 0x10000
	s_addc_u32 s69, s69, 0
	s_cmp_gt_u32 s70, 61
	s_cbranch_scc0 .LBB0_757
	s_and_b64 vcc, exec, s[12:13]
	s_cbranch_vccz .LBB0_760
	s_barrier

; #define PG8_STAGE(bufoff, gbase, voff) do { _Pragma("unroll") for (int _i = 0; _i < 2; ++_i) \
;         __builtin_amdgcn_global_load_lds((const unsigned*)((const char*)(gbase) + (voff)[_i]), (PG8_LAS unsigned*)(lds + (bufoff) + ldsw + _i * 8192), 16, 0, 0); } while (0)
; #define PG8_LDA(dst, b, h) do { _Pragma("unroll") for (int m = 0; m < 4; ++m) _Pragma("unroll") for (int k = 0; k < 2; ++k) dst[m][k] = *(const PG8_LAS bf16x8*)(lds + PG8_SA(b, h) + aoff + m * 2048 + k * 1024); } while (0)
; #define PG8_LDB(dst, b, h) do { _Pragma("unroll") for (int n = 0; n < 2; ++n) _Pragma("unroll") for (int k = 0; k < 2; ++k) dst[n][k] = *(const PG8_LAS bf16x8*)(lds + PG8_SB(b, h) + boff + n * 2048 + k * 1024); } while (0)
; #define PG8_MMA(ai, bj, At, Bt) do { __builtin_amdgcn_s_setprio(1); _Pragma("unroll") for (int m = 0; m < 4; ++m) _Pragma("unroll") for (int n = 0; n < 2; ++n) _Pragma("unroll") for (int k = 0; k < 2; ++k) \
;         acc[ai][bj][m][n] = __builtin_amdgcn_mfma_f32_16x16x32_bf16(Bt[n][k], At[m][k], acc[ai][bj][m][n], 0, 0, 0); __builtin_amdgcn_s_setprio(0); } while (0)
; #define PG8_WAIT_V(n) asm volatile("s_waitcnt vmcnt(" #n ")" ::: "memory")
; #define PG8_WAIT_L(n) asm volatile("s_waitcnt lgkmcnt(" #n ")" ::: "memory")
; template <class Epi, class Sched, bool ALIGN_EPI = false, bool SP2 = false>
; __device__ __forceinline__ void gemm_phase(PG8_LAS unsigned char* lds, const Gemm g, const Sched& S, const Epi& E) {
;     ...
;         for (; t < tend; t += 2) {
;             const bool last = (t == nt - 2);
;             const char* a1 = cA + (size_t)(t + 1) * kstep;
;             const char* a2 = last ? nA : cA + (size_t)(t + 2) * kstep; const char* b2 = last ? nB : cB + (size_t)(t + 2) * kstep;
;             const char* a3 = a2 + kstep; const char* b3 = b2 + kstep;
;             if (last && has_next) S.a_ready(nxt);
;             if constexpr (SP2) {
;             PG8_LDB(B0, 0, 0); PG8_LDB(B1, 0, 1); PG8_SCHED; PG8_LDA(At, 0, 0); PG8_STAGE(PG8_SA(1, 1), a1 + hstep, voffA);
;             PG8_WAIT_V(8); PG8_WAIT_L(0); PG8_BAR; PG8_MMA(0, 0, At, B0); PG8_MMA(0, 1, At, B1); PG8_BAR; PG8_SCHED;
;             PG8_LDA(At, 0, 1); PG8_STAGE(PG8_SB(0, 0), b2, voffB); PG8_STAGE(PG8_SB(0, 1), b2 + hstep, voffB); PG8_STAGE(PG8_SA(0, 0), a2, voffA);
;             PG8_WAIT_V(8); PG8_WAIT_L(0); PG8_BAR; PG8_MMA(1, 0, At, B0); PG8_MMA(1, 1, At, B1); PG8_BAR; PG8_SCHED;
.LBB0_840:
	ds_read_b128 v[148:151], v153
	ds_read_b128 v[158:161], v153 offset:1024
	ds_read_b128 v[162:165], v153 offset:2048
	ds_read_b128 v[166:169], v153 offset:3072
	ds_read_b128 v[170:173], v154
	ds_read_b128 v[174:177], v154 offset:1024
	ds_read_b128 v[180:183], v154 offset:2048
	ds_read_b128 v[184:187], v154 offset:3072
	s_add_u32 s42, s40, 0x4000
	s_addc_u32 s43, s41, 0
	s_cmp_eq_u32 s69, 60
	s_cselect_b32 s46, s65, s42
	s_cselect_b32 s47, s23, s43
	s_cselect_b32 s44, s66, s67
	s_cselect_b32 s45, s17, s68
	s_add_u32 s42, s46, 0x8000
	s_addc_u32 s43, s47, 0
	s_sub_u32 s42, s40, 0x4000
	s_subb_u32 s43, s41, 0
	v_lshl_add_u64 v[226:227], s[42:43], 0, v[130:131]
	s_mov_b32 m0, s50
	s_nop 0
	global_load_lds_dwordx4 v[226:227], off
	v_lshl_add_u64 v[226:227], s[42:43], 0, v[134:135]
	s_mov_b32 m0, s51
	s_nop 0
	global_load_lds_dwordx4 v[226:227], off
	v_lshl_add_u64 v[226:227], s[40:41], 0, v[140:141]
	s_add_i32 m0, s28, 0xc000
	ds_read_b128 v[188:191], v155
	ds_read_b128 v[198:201], v155 offset:1024
	ds_read_b128 v[202:205], v155 offset:2048
	ds_read_b128 v[206:209], v155 offset:3072
	ds_read_b128 v[210:213], v155 offset:4096
	ds_read_b128 v[214:217], v155 offset:5120
	ds_read_b128 v[218:221], v155 offset:6144
	ds_read_b128 v[222:225], v155 offset:7168
	global_load_lds_dwordx4 v[226:227], off
	v_lshl_add_u64 v[226:227], s[40:41], 0, v[142:143]
	s_add_i32 m0, s28, 0xe000
	s_nop 0
	global_load_lds_dwordx4 v[226:227], off
	s_waitcnt vmcnt(8)
	s_waitcnt lgkmcnt(0)
	s_barrier
	s_setprio 1
	s_waitcnt lgkmcnt(0)
	v_mfma_f32_16x16x32_bf16 v[126:129], v[148:151], v[188:191], v[126:129]
	v_mfma_f32_16x16x32_bf16 v[126:129], v[158:161], v[198:201], v[126:129]
	v_mfma_f32_16x16x32_bf16 v[122:125], v[162:165], v[188:191], v[122:125]
	v_mfma_f32_16x16x32_bf16 v[122:125], v[166:169], v[198:201], v[122:125]
	v_mfma_f32_16x16x32_bf16 v[118:121], v[170:173], v[188:191], v[118:121]
	v_mfma_f32_16x16x32_bf16 v[118:121], v[174:177], v[198:201], v[118:121]
	v_mfma_f32_16x16x32_bf16 v[114:117], v[180:183], v[188:191], v[114:117]
	v_mfma_f32_16x16x32_bf16 v[114:117], v[184:187], v[198:201], v[114:117]
	v_mfma_f32_16x16x32_bf16 v[110:113], v[148:151], v[202:205], v[110:113]
	v_mfma_f32_16x16x32_bf16 v[110:113], v[158:161], v[206:209], v[110:113]
	v_mfma_f32_16x16x32_bf16 v[106:109], v[162:165], v[202:205], v[106:109]
	v_mfma_f32_16x16x32_bf16 v[106:109], v[166:169], v[206:209], v[106:109]
	v_mfma_f32_16x16x32_bf16 v[102:105], v[170:173], v[202:205], v[102:105]
	v_mfma_f32_16x16x32_bf16 v[102:105], v[174:177], v[206:209], v[102:105]
	v_mfma_f32_16x16x32_bf16 v[98:101], v[180:183], v[202:205], v[98:101]
	v_mfma_f32_16x16x32_bf16 v[98:101], v[184:187], v[206:209], v[98:101]
	s_setprio 0
	s_setprio 1
	v_mfma_f32_16x16x32_bf16 v[94:97], v[148:151], v[210:213], v[94:97]
	v_mfma_f32_16x16x32_bf16 v[94:97], v[158:161], v[214:217], v[94:97]
	v_mfma_f32_16x16x32_bf16 v[90:93], v[162:165], v[210:213], v[90:93]
	v_mfma_f32_16x16x32_bf16 v[90:93], v[166:169], v[214:217], v[90:93]
	v_mfma_f32_16x16x32_bf16 v[86:89], v[170:173], v[210:213], v[86:89]
	v_mfma_f32_16x16x32_bf16 v[86:89], v[174:177], v[214:217], v[86:89]
	v_mfma_f32_16x16x32_bf16 v[82:85], v[180:183], v[210:213], v[82:85]
	v_mfma_f32_16x16x32_bf16 v[82:85], v[184:187], v[214:217], v[82:85]
	v_mfma_f32_16x16x32_bf16 v[78:81], v[148:151], v[218:221], v[78:81]
	v_mfma_f32_16x16x32_bf16 v[78:81], v[158:161], v[222:225], v[78:81]
	v_mfma_f32_16x16x32_bf16 v[74:77], v[162:165], v[218:221], v[74:77]
	v_mfma_f32_16x16x32_bf16 v[74:77], v[166:169], v[222:225], v[74:77]
	v_mfma_f32_16x16x32_bf16 v[70:73], v[170:173], v[218:221], v[70:73]
	v_mfma_f32_16x16x32_bf16 v[70:73], v[174:177], v[222:225], v[70:73]
	v_mfma_f32_16x16x32_bf16 v[66:69], v[180:183], v[218:221], v[66:69]
	v_mfma_f32_16x16x32_bf16 v[66:69], v[184:187], v[222:225], v[66:69]
	s_setprio 0
	s_barrier
	s_add_i32 s70, s56, s3
	v_lshl_add_u64 v[226:227], s[44:45], 0, v[132:133]
	s_mov_b32 m0, s70
	ds_read_b128 v[188:191], v155 offset:16384
	ds_read_b128 v[198:201], v155 offset:17408
	ds_read_b128 v[202:205], v155 offset:18432
	ds_read_b128 v[206:209], v155 offset:19456
	ds_read_b128 v[210:213], v155 offset:20480
	ds_read_b128 v[214:217], v155 offset:21504
	ds_read_b128 v[218:221], v155 offset:22528
	ds_read_b128 v[222:225], v155 offset:23552
	global_load_lds_dwordx4 v[226:227], off
	s_add_i32 m0, s70, 0x2000
	s_add_u32 s70, s44, 0x4000
	v_lshl_add_u64 v[226:227], s[44:45], 0, v[136:137]
	s_addc_u32 s71, s45, 0
	s_add_i32 s72, s57, s3
	global_load_lds_dwordx4 v[226:227], off
	v_lshl_add_u64 v[226:227], s[70:71], 0, v[132:133]
	s_mov_b32 m0, s72
	s_nop 0
	global_load_lds_dwordx4 v[226:227], off
	v_lshl_add_u64 v[226:227], s[70:71], 0, v[136:137]
	s_add_i32 m0, s72, 0x2000
	s_nop 0
	global_load_lds_dwordx4 v[226:227], off
	s_waitcnt vmcnt(6)
	s_waitcnt lgkmcnt(0)
	s_barrier
; #define PG8_STAGE(bufoff, gbase, voff) do { _Pragma("unroll") for (int _i = 0; _i < 2; ++_i) \
;         __builtin_amdgcn_global_load_lds((const unsigned*)((const char*)(gbase) + (voff)[_i]), (PG8_LAS unsigned*)(lds + (bufoff) + ldsw + _i * 8192), 16, 0, 0); } while (0)
; #define PG8_LDA(dst, b, h) do { _Pragma("unroll") for (int m = 0; m < 4; ++m) _Pragma("unroll") for (int k = 0; k < 2; ++k) dst[m][k] = *(const PG8_LAS bf16x8*)(lds + PG8_SA(b, h) + aoff + m * 2048 + k * 1024); } while (0)
; #define PG8_LDB(dst, b, h) do { _Pragma("unroll") for (int n = 0; n < 2; ++n) _Pragma("unroll") for (int k = 0; k < 2; ++k) dst[n][k] = *(const PG8_LAS bf16x8*)(lds + PG8_SB(b, h) + boff + n * 2048 + k * 1024); } while (0)
; #define PG8_MMA(ai, bj, At, Bt) do { __builtin_amdgcn_s_setprio(1); _Pragma("unroll") for (int m = 0; m < 4; ++m) _Pragma("unroll") for (int n = 0; n < 2; ++n) _Pragma("unroll") for (int k = 0; k < 2; ++k) \
;         acc[ai][bj][m][n] = __builtin_amdgcn_mfma_f32_16x16x32_bf16(Bt[n][k], At[m][k], acc[ai][bj][m][n], 0, 0, 0); __builtin_amdgcn_s_setprio(0); } while (0)
; #define PG8_WAIT_V(n) asm volatile("s_waitcnt vmcnt(" #n ")" ::: "memory")
; #define PG8_WAIT_L(n) asm volatile("s_waitcnt lgkmcnt(" #n ")" ::: "memory")
; #define PG8_BAR __builtin_amdgcn_s_barrier()
; #define PG8_SCHED __builtin_amdgcn_sched_barrier(0)
; template <class Epi, class Sched, bool ALIGN_EPI = false, bool SP2 = false>
; __device__ __forceinline__ void gemm_phase(PG8_LAS unsigned char* lds, const Gemm g, const Sched& S, const Epi& E) {
;     ...
;             PG8_WAIT_V(8); PG8_WAIT_L(0); PG8_BAR; PG8_MMA(1, 0, At, B0); PG8_MMA(1, 1, At, B1); PG8_BAR; PG8_SCHED;
;             PG8_LDB(B0, 1, 0); PG8_LDB(B1, 1, 1); PG8_SCHED; PG8_LDA(At, 1, 0); PG8_STAGE(PG8_SA(0, 1), a2 + hstep, voffA);
;             PG8_WAIT_V(8); PG8_WAIT_L(0); PG8_BAR; PG8_MMA(0, 0, At, B0); PG8_MMA(0, 1, At, B1); PG8_BAR; PG8_SCHED;
	s_setprio 1
	s_waitcnt lgkmcnt(0)
	v_mfma_f32_16x16x32_bf16 v[62:65], v[148:151], v[188:191], v[62:65]
	v_mfma_f32_16x16x32_bf16 v[62:65], v[158:161], v[198:201], v[62:65]
	v_mfma_f32_16x16x32_bf16 v[58:61], v[162:165], v[188:191], v[58:61]
	v_mfma_f32_16x16x32_bf16 v[58:61], v[166:169], v[198:201], v[58:61]
	v_mfma_f32_16x16x32_bf16 v[54:57], v[170:173], v[188:191], v[54:57]
	v_mfma_f32_16x16x32_bf16 v[54:57], v[174:177], v[198:201], v[54:57]
	v_mfma_f32_16x16x32_bf16 v[50:53], v[180:183], v[188:191], v[50:53]
	v_mfma_f32_16x16x32_bf16 v[50:53], v[184:187], v[198:201], v[50:53]
	v_mfma_f32_16x16x32_bf16 v[46:49], v[148:151], v[202:205], v[46:49]
	v_mfma_f32_16x16x32_bf16 v[46:49], v[158:161], v[206:209], v[46:49]
	v_mfma_f32_16x16x32_bf16 v[42:45], v[162:165], v[202:205], v[42:45]
	v_mfma_f32_16x16x32_bf16 v[42:45], v[166:169], v[206:209], v[42:45]
	v_mfma_f32_16x16x32_bf16 v[38:41], v[170:173], v[202:205], v[38:41]
	v_mfma_f32_16x16x32_bf16 v[38:41], v[174:177], v[206:209], v[38:41]
	v_mfma_f32_16x16x32_bf16 v[34:37], v[180:183], v[202:205], v[34:37]
	v_mfma_f32_16x16x32_bf16 v[34:37], v[184:187], v[206:209], v[34:37]
	s_setprio 0
	s_setprio 1
	v_mfma_f32_16x16x32_bf16 v[30:33], v[148:151], v[210:213], v[30:33]
	v_mfma_f32_16x16x32_bf16 v[30:33], v[158:161], v[214:217], v[30:33]
	v_mfma_f32_16x16x32_bf16 v[26:29], v[162:165], v[210:213], v[26:29]
	v_mfma_f32_16x16x32_bf16 v[26:29], v[166:169], v[214:217], v[26:29]
	v_mfma_f32_16x16x32_bf16 v[22:25], v[170:173], v[210:213], v[22:25]
	v_mfma_f32_16x16x32_bf16 v[22:25], v[174:177], v[214:217], v[22:25]
	v_mfma_f32_16x16x32_bf16 v[18:21], v[180:183], v[210:213], v[18:21]
	v_mfma_f32_16x16x32_bf16 v[18:21], v[184:187], v[214:217], v[18:21]
	v_mfma_f32_16x16x32_bf16 v[14:17], v[148:151], v[218:221], v[14:17]
	v_mfma_f32_16x16x32_bf16 v[14:17], v[158:161], v[222:225], v[14:17]
	v_mfma_f32_16x16x32_bf16 v[10:13], v[162:165], v[218:221], v[10:13]
	v_mfma_f32_16x16x32_bf16 v[10:13], v[166:169], v[222:225], v[10:13]
	v_mfma_f32_16x16x32_bf16 v[6:9], v[170:173], v[218:221], v[6:9]
	v_mfma_f32_16x16x32_bf16 v[6:9], v[174:177], v[222:225], v[6:9]
	v_mfma_f32_16x16x32_bf16 v[2:5], v[180:183], v[218:221], v[2:5]
	v_mfma_f32_16x16x32_bf16 v[2:5], v[184:187], v[222:225], v[2:5]
	s_setprio 0
	s_barrier
	s_add_i32 s70, 0, 0x18000
	v_add_u32_e32 v138, s70, v1
	s_add_i32 s71, 0, 0x1c000
	ds_read_b128 v[148:151], v138
	ds_read_b128 v[158:161], v138 offset:1024
	ds_read_b128 v[162:165], v138 offset:2048
	ds_read_b128 v[166:169], v138 offset:3072
	v_add_u32_e32 v138, s71, v1
	ds_read_b128 v[170:173], v138
	ds_read_b128 v[174:177], v138 offset:1024
	ds_read_b128 v[180:183], v138 offset:2048
	ds_read_b128 v[184:187], v138 offset:3072
	v_lshl_add_u64 v[226:227], s[46:47], 0, v[130:131]
	s_mov_b32 m0, s28
	s_nop 0
	global_load_lds_dwordx4 v[226:227], off
	v_lshl_add_u64 v[226:227], s[46:47], 0, v[134:135]
	s_mov_b32 m0, s29
	s_nop 0
	global_load_lds_dwordx4 v[226:227], off
	s_add_u32 s46, s46, 0x4000
	s_addc_u32 s47, s47, 0
	s_mov_b32 m0, s30
	v_lshl_add_u64 v[226:227], s[46:47], 0, v[130:131]
	ds_read_b128 v[188:191], v155 offset:32768
	ds_read_b128 v[198:201], v155 offset:33792
	ds_read_b128 v[202:205], v155 offset:34816
	ds_read_b128 v[206:209], v155 offset:35840
	ds_read_b128 v[210:213], v155 offset:36864
	ds_read_b128 v[214:217], v155 offset:37888
	ds_read_b128 v[218:221], v155 offset:38912
	ds_read_b128 v[222:225], v155 offset:39936
	global_load_lds_dwordx4 v[226:227], off
	v_lshl_add_u64 v[226:227], s[46:47], 0, v[134:135]
	s_mov_b32 m0, s31
	s_nop 0
	global_load_lds_dwordx4 v[226:227], off
	s_waitcnt vmcnt(8)
	s_waitcnt lgkmcnt(0)
	s_barrier
; #define PG8_STAGE(bufoff, gbase, voff) do { _Pragma("unroll") for (int _i = 0; _i < 2; ++_i) \
;         __builtin_amdgcn_global_load_lds((const unsigned*)((const char*)(gbase) + (voff)[_i]), (PG8_LAS unsigned*)(lds + (bufoff) + ldsw + _i * 8192), 16, 0, 0); } while (0)
; #define PG8_LDA(dst, b, h) do { _Pragma("unroll") for (int m = 0; m < 4; ++m) _Pragma("unroll") for (int k = 0; k < 2; ++k) dst[m][k] = *(const PG8_LAS bf16x8*)(lds + PG8_SA(b, h) + aoff + m * 2048 + k * 1024); } while (0)
; #define PG8_MMA(ai, bj, At, Bt) do { __builtin_amdgcn_s_setprio(1); _Pragma("unroll") for (int m = 0; m < 4; ++m) _Pragma("unroll") for (int n = 0; n < 2; ++n) _Pragma("unroll") for (int k = 0; k < 2; ++k) \
;         acc[ai][bj][m][n] = __builtin_amdgcn_mfma_f32_16x16x32_bf16(Bt[n][k], At[m][k], acc[ai][bj][m][n], 0, 0, 0); __builtin_amdgcn_s_setprio(0); } while (0)
; #define PG8_WAIT_V(n) asm volatile("s_waitcnt vmcnt(" #n ")" ::: "memory")
; #define PG8_WAIT_L(n) asm volatile("s_waitcnt lgkmcnt(" #n ")" ::: "memory")
; #define PG8_BAR __builtin_amdgcn_s_barrier()
; #define PG8_SCHED __builtin_amdgcn_sched_barrier(0)
; template <class Epi, class Sched, bool ALIGN_EPI = false, bool SP2 = false>
; __device__ __forceinline__ void gemm_phase(PG8_LAS unsigned char* lds, const Gemm g, const Sched& S, const Epi& E) {
;     ...
;             PG8_WAIT_V(8); PG8_WAIT_L(0); PG8_BAR; PG8_MMA(0, 0, At, B0); PG8_MMA(0, 1, At, B1); PG8_BAR; PG8_SCHED;
;             PG8_LDA(At, 1, 1); PG8_STAGE(PG8_SB(1, 0), b3, voffB); PG8_STAGE(PG8_SB(1, 1), b3 + hstep, voffB); PG8_STAGE(PG8_SA(1, 0), a3, voffA);
;             PG8_WAIT_V(8); PG8_WAIT_L(0); PG8_BAR; PG8_MMA(1, 0, At, B0); PG8_MMA(1, 1, At, B1); PG8_BAR; PG8_SCHED;
	s_setprio 1
	s_waitcnt lgkmcnt(0)
	v_mfma_f32_16x16x32_bf16 v[126:129], v[148:151], v[188:191], v[126:129]
	v_mfma_f32_16x16x32_bf16 v[126:129], v[158:161], v[198:201], v[126:129]
	v_mfma_f32_16x16x32_bf16 v[122:125], v[162:165], v[188:191], v[122:125]
	v_mfma_f32_16x16x32_bf16 v[122:125], v[166:169], v[198:201], v[122:125]
	v_mfma_f32_16x16x32_bf16 v[118:121], v[170:173], v[188:191], v[118:121]
	v_mfma_f32_16x16x32_bf16 v[118:121], v[174:177], v[198:201], v[118:121]
	v_mfma_f32_16x16x32_bf16 v[114:117], v[180:183], v[188:191], v[114:117]
	v_mfma_f32_16x16x32_bf16 v[114:117], v[184:187], v[198:201], v[114:117]
	v_mfma_f32_16x16x32_bf16 v[110:113], v[148:151], v[202:205], v[110:113]
	v_mfma_f32_16x16x32_bf16 v[110:113], v[158:161], v[206:209], v[110:113]
	v_mfma_f32_16x16x32_bf16 v[106:109], v[162:165], v[202:205], v[106:109]
	v_mfma_f32_16x16x32_bf16 v[106:109], v[166:169], v[206:209], v[106:109]
	v_mfma_f32_16x16x32_bf16 v[102:105], v[170:173], v[202:205], v[102:105]
	v_mfma_f32_16x16x32_bf16 v[102:105], v[174:177], v[206:209], v[102:105]
	v_mfma_f32_16x16x32_bf16 v[98:101], v[180:183], v[202:205], v[98:101]
	v_mfma_f32_16x16x32_bf16 v[98:101], v[184:187], v[206:209], v[98:101]
	s_setprio 0
	s_setprio 1
	v_mfma_f32_16x16x32_bf16 v[94:97], v[148:151], v[210:213], v[94:97]
	v_mfma_f32_16x16x32_bf16 v[94:97], v[158:161], v[214:217], v[94:97]
	v_mfma_f32_16x16x32_bf16 v[90:93], v[162:165], v[210:213], v[90:93]
	v_mfma_f32_16x16x32_bf16 v[90:93], v[166:169], v[214:217], v[90:93]
	v_mfma_f32_16x16x32_bf16 v[86:89], v[170:173], v[210:213], v[86:89]
	v_mfma_f32_16x16x32_bf16 v[86:89], v[174:177], v[214:217], v[86:89]
	v_mfma_f32_16x16x32_bf16 v[82:85], v[180:183], v[210:213], v[82:85]
	v_mfma_f32_16x16x32_bf16 v[82:85], v[184:187], v[214:217], v[82:85]
	v_mfma_f32_16x16x32_bf16 v[78:81], v[148:151], v[218:221], v[78:81]
	v_mfma_f32_16x16x32_bf16 v[78:81], v[158:161], v[222:225], v[78:81]
	v_mfma_f32_16x16x32_bf16 v[74:77], v[162:165], v[218:221], v[74:77]
	v_mfma_f32_16x16x32_bf16 v[74:77], v[166:169], v[222:225], v[74:77]
	v_mfma_f32_16x16x32_bf16 v[70:73], v[170:173], v[218:221], v[70:73]
	v_mfma_f32_16x16x32_bf16 v[70:73], v[174:177], v[222:225], v[70:73]
	v_mfma_f32_16x16x32_bf16 v[66:69], v[180:183], v[218:221], v[66:69]
	v_mfma_f32_16x16x32_bf16 v[66:69], v[184:187], v[222:225], v[66:69]
	s_setprio 0
	s_barrier
	s_add_u32 s46, s44, 0x8000
	s_addc_u32 s47, s45, 0
	s_add_i32 s70, s70, s3
	v_lshl_add_u64 v[226:227], s[46:47], 0, v[132:133]
	s_mov_b32 m0, s70
	ds_read_b128 v[188:191], v155 offset:49152
	ds_read_b128 v[198:201], v155 offset:50176
	ds_read_b128 v[202:205], v155 offset:51200
	ds_read_b128 v[206:209], v155 offset:52224
	ds_read_b128 v[210:213], v155 offset:53248
	ds_read_b128 v[214:217], v155 offset:54272
	ds_read_b128 v[218:221], v155 offset:55296
	ds_read_b128 v[222:225], v155 offset:56320
	global_load_lds_dwordx4 v[226:227], off
	s_add_i32 m0, s70, 0x2000
	s_add_u32 s44, s44, 0xc000
	v_lshl_add_u64 v[226:227], s[46:47], 0, v[136:137]
	s_addc_u32 s45, s45, 0
	s_add_i32 s46, s71, s3
	global_load_lds_dwordx4 v[226:227], off
	v_lshl_add_u64 v[226:227], s[44:45], 0, v[132:133]
	s_mov_b32 m0, s46
	s_nop 0
	global_load_lds_dwordx4 v[226:227], off
	v_lshl_add_u64 v[226:227], s[44:45], 0, v[136:137]
	s_add_i32 m0, s46, 0x2000
	s_nop 0
	global_load_lds_dwordx4 v[226:227], off
	s_waitcnt vmcnt(6)
	s_waitcnt lgkmcnt(0)
	s_barrier
	s_setprio 1
	s_waitcnt lgkmcnt(0)
	v_mfma_f32_16x16x32_bf16 v[62:65], v[148:151], v[188:191], v[62:65]
	v_mfma_f32_16x16x32_bf16 v[62:65], v[158:161], v[198:201], v[62:65]
	v_mfma_f32_16x16x32_bf16 v[58:61], v[162:165], v[188:191], v[58:61]
	v_mfma_f32_16x16x32_bf16 v[58:61], v[166:169], v[198:201], v[58:61]
	v_mfma_f32_16x16x32_bf16 v[54:57], v[170:173], v[188:191], v[54:57]
	v_mfma_f32_16x16x32_bf16 v[54:57], v[174:177], v[198:201], v[54:57]
	v_mfma_f32_16x16x32_bf16 v[50:53], v[180:183], v[188:191], v[50:53]
	v_mfma_f32_16x16x32_bf16 v[50:53], v[184:187], v[198:201], v[50:53]
	v_mfma_f32_16x16x32_bf16 v[46:49], v[148:151], v[202:205], v[46:49]
	v_mfma_f32_16x16x32_bf16 v[46:49], v[158:161], v[206:209], v[46:49]
	v_mfma_f32_16x16x32_bf16 v[42:45], v[162:165], v[202:205], v[42:45]
	v_mfma_f32_16x16x32_bf16 v[42:45], v[166:169], v[206:209], v[42:45]
	v_mfma_f32_16x16x32_bf16 v[38:41], v[170:173], v[202:205], v[38:41]
	v_mfma_f32_16x16x32_bf16 v[38:41], v[174:177], v[206:209], v[38:41]
	v_mfma_f32_16x16x32_bf16 v[34:37], v[180:183], v[202:205], v[34:37]
	v_mfma_f32_16x16x32_bf16 v[34:37], v[184:187], v[206:209], v[34:37]
	s_setprio 0
	s_setprio 1
	v_mfma_f32_16x16x32_bf16 v[30:33], v[148:151], v[210:213], v[30:33]
	v_mfma_f32_16x16x32_bf16 v[30:33], v[158:161], v[214:217], v[30:33]
	v_mfma_f32_16x16x32_bf16 v[26:29], v[162:165], v[210:213], v[26:29]
	v_mfma_f32_16x16x32_bf16 v[26:29], v[166:169], v[214:217], v[26:29]
	v_mfma_f32_16x16x32_bf16 v[22:25], v[170:173], v[210:213], v[22:25]
	v_mfma_f32_16x16x32_bf16 v[22:25], v[174:177], v[214:217], v[22:25]
	v_mfma_f32_16x16x32_bf16 v[18:21], v[180:183], v[210:213], v[18:21]
	v_mfma_f32_16x16x32_bf16 v[18:21], v[184:187], v[214:217], v[18:21]
	v_mfma_f32_16x16x32_bf16 v[14:17], v[148:151], v[218:221], v[14:17]
	v_mfma_f32_16x16x32_bf16 v[14:17], v[158:161], v[222:225], v[14:17]
	v_mfma_f32_16x16x32_bf16 v[10:13], v[162:165], v[218:221], v[10:13]
	v_mfma_f32_16x16x32_bf16 v[10:13], v[166:169], v[222:225], v[10:13]
	v_mfma_f32_16x16x32_bf16 v[6:9], v[170:173], v[218:221], v[6:9]
	v_mfma_f32_16x16x32_bf16 v[6:9], v[174:177], v[222:225], v[6:9]
	v_mfma_f32_16x16x32_bf16 v[2:5], v[180:183], v[218:221], v[2:5]
	v_mfma_f32_16x16x32_bf16 v[2:5], v[184:187], v[222:225], v[2:5]
	s_setprio 0
	s_barrier
	s_add_i32 s69, s69, 2
	s_add_u32 s40, s40, 0x10000
	s_addc_u32 s41, s41, 0
	s_add_u32 s67, s67, 0x10000
	s_addc_u32 s68, s68, 0
	s_cmp_gt_u32 s69, 61
	s_cbranch_scc0 .LBB0_840
	s_and_b64 vcc, exec, s[14:15]
	s_cbranch_vccz .LBB0_843
	s_barrier

; #define PG8_STAGE(bufoff, gbase, voff) do { _Pragma("unroll") for (int _i = 0; _i < 2; ++_i) \
;         __builtin_amdgcn_global_load_lds((const unsigned*)((const char*)(gbase) + (voff)[_i]), (PG8_LAS unsigned*)(lds + (bufoff) + ldsw + _i * 8192), 16, 0, 0); } while (0)
; #define PG8_LDA(dst, b, h) do { _Pragma("unroll") for (int m = 0; m < 4; ++m) _Pragma("unroll") for (int k = 0; k < 2; ++k) dst[m][k] = *(const PG8_LAS bf16x8*)(lds + PG8_SA(b, h) + aoff + m * 2048 + k * 1024); } while (0)
; #define PG8_LDB(dst, b, h) do { _Pragma("unroll") for (int n = 0; n < 2; ++n) _Pragma("unroll") for (int k = 0; k < 2; ++k) dst[n][k] = *(const PG8_LAS bf16x8*)(lds + PG8_SB(b, h) + boff + n * 2048 + k * 1024); } while (0)
; #define PG8_MMA(ai, bj, At, Bt) do { __builtin_amdgcn_s_setprio(1); _Pragma("unroll") for (int m = 0; m < 4; ++m) _Pragma("unroll") for (int n = 0; n < 2; ++n) _Pragma("unroll") for (int k = 0; k < 2; ++k) \
;         acc[ai][bj][m][n] = __builtin_amdgcn_mfma_f32_16x16x32_bf16(Bt[n][k], At[m][k], acc[ai][bj][m][n], 0, 0, 0); __builtin_amdgcn_s_setprio(0); } while (0)
; #define PG8_WAIT_V(n) asm volatile("s_waitcnt vmcnt(" #n ")" ::: "memory")
; #define PG8_WAIT_L(n) asm volatile("s_waitcnt lgkmcnt(" #n ")" ::: "memory")
; #define PG8_BAR __builtin_amdgcn_s_barrier()
; #define PG8_SCHED __builtin_amdgcn_sched_barrier(0)
; template <class Epi, class Sched, bool ALIGN_EPI = false, bool SP2 = false>
; __device__ __forceinline__ void gemm_phase(PG8_LAS unsigned char* lds, const Gemm g, const Sched& S, const Epi& E) {
;     ...
;             const bool last = (t == nt - 2);
;             const char* a1 = cA + (size_t)(t + 1) * kstep;
;             const char* a2 = last ? nA : cA + (size_t)(t + 2) * kstep; const char* b2 = last ? nB : cB + (size_t)(t + 2) * kstep;
;             const char* a3 = a2 + kstep; const char* b3 = b2 + kstep;
;             if (last && has_next) S.a_ready(nxt);
;             if constexpr (SP2) {
;             PG8_LDB(B0, 0, 0); PG8_LDB(B1, 0, 1); PG8_SCHED; PG8_LDA(At, 0, 0); PG8_STAGE(PG8_SA(1, 1), a1 + hstep, voffA);
;             PG8_WAIT_V(8); PG8_WAIT_L(0); PG8_BAR; PG8_MMA(0, 0, At, B0); PG8_MMA(0, 1, At, B1); PG8_BAR; PG8_SCHED;
;             PG8_LDA(At, 0, 1); PG8_STAGE(PG8_SB(0, 0), b2, voffB); PG8_STAGE(PG8_SB(0, 1), b2 + hstep, voffB); PG8_STAGE(PG8_SA(0, 0), a2, voffA);
.LBB0_939:
	s_or_b32 s24, s59, 1
	s_lshl_b64 s[62:63], s[24:25], 15
	s_add_i32 s24, s59, 2
	ds_read_b128 v[156:159], v193
	ds_read_b128 v[160:163], v193 offset:1024
	ds_read_b128 v[196:199], v193 offset:2048
	ds_read_b128 v[200:203], v193 offset:3072
	ds_read_b128 v[204:207], v194
	ds_read_b128 v[208:211], v194 offset:1024
	ds_read_b128 v[212:215], v194 offset:2048
	ds_read_b128 v[216:219], v194 offset:3072
	s_lshl_b64 s[8:9], s[24:25], 15
	s_add_u32 s44, s6, s8
	s_addc_u32 s45, s7, s9
	s_cmpk_eq_i32 s59, 0xaa
	s_cselect_b32 s46, s58, s44
	s_cselect_b32 s47, s56, s45
	s_cselect_b32 s44, 0, s8
	s_cselect_b32 s45, 0, s9
	s_add_u32 s8, s46, 0x8000
	s_addc_u32 s9, s47, 0
	s_add_u32 s44, s14, s44
	s_addc_u32 s45, s15, s45
	s_add_u32 s62, s6, s62
	s_addc_u32 s63, s7, s63
	s_add_u32 s62, s62, 0x4000
	s_addc_u32 s63, s63, 0
	s_sub_u32 s8, s62, 0x4000
	s_subb_u32 s9, s63, 0
	v_lshl_add_u64 v[164:165], s[8:9], 0, v[130:131]
	s_mov_b32 m0, s51
	s_nop 0
	global_load_lds_dwordx4 v[164:165], off
	v_lshl_add_u64 v[164:165], s[8:9], 0, v[134:135]
	s_mov_b32 m0, s57
	s_nop 0
	global_load_lds_dwordx4 v[164:165], off
	v_lshl_add_u64 v[164:165], s[62:63], 0, v[130:131]
	s_add_i32 m0, s30, 0xc000
	ds_read_b128 v[220:223], v186
	ds_read_b128 v[224:227], v186 offset:1024
	ds_read_b128 v[228:231], v186 offset:2048
	ds_read_b128 v[232:235], v186 offset:3072
	ds_read_b128 v[236:239], v186 offset:4096
	ds_read_b128 v[240:243], v186 offset:5120
	ds_read_b128 v[244:247], v186 offset:6144
	ds_read_b128 v[248:251], v186 offset:7168
	global_load_lds_dwordx4 v[164:165], off
	v_lshl_add_u64 v[164:165], s[62:63], 0, v[134:135]
	s_add_i32 m0, s30, 0xe000
	s_nop 0
	global_load_lds_dwordx4 v[164:165], off
	s_waitcnt vmcnt(8)
	s_waitcnt lgkmcnt(0)
	s_barrier
	s_setprio 1
	s_waitcnt lgkmcnt(0)
	v_mfma_f32_16x16x32_bf16 v[126:129], v[156:159], v[220:223], v[126:129]
	v_mfma_f32_16x16x32_bf16 v[126:129], v[160:163], v[224:227], v[126:129]
	v_mfma_f32_16x16x32_bf16 v[122:125], v[196:199], v[220:223], v[122:125]
	v_mfma_f32_16x16x32_bf16 v[122:125], v[200:203], v[224:227], v[122:125]
	v_mfma_f32_16x16x32_bf16 v[118:121], v[204:207], v[220:223], v[118:121]
	v_mfma_f32_16x16x32_bf16 v[118:121], v[208:211], v[224:227], v[118:121]
	v_mfma_f32_16x16x32_bf16 v[114:117], v[212:215], v[220:223], v[114:117]
	v_mfma_f32_16x16x32_bf16 v[114:117], v[216:219], v[224:227], v[114:117]
	v_mfma_f32_16x16x32_bf16 v[110:113], v[156:159], v[228:231], v[110:113]
	v_mfma_f32_16x16x32_bf16 v[110:113], v[160:163], v[232:235], v[110:113]
	v_mfma_f32_16x16x32_bf16 v[106:109], v[196:199], v[228:231], v[106:109]
	v_mfma_f32_16x16x32_bf16 v[106:109], v[200:203], v[232:235], v[106:109]
	v_mfma_f32_16x16x32_bf16 v[102:105], v[204:207], v[228:231], v[102:105]
	v_mfma_f32_16x16x32_bf16 v[102:105], v[208:211], v[232:235], v[102:105]
	v_mfma_f32_16x16x32_bf16 v[98:101], v[212:215], v[228:231], v[98:101]
	v_mfma_f32_16x16x32_bf16 v[98:101], v[216:219], v[232:235], v[98:101]
	s_setprio 0
	s_setprio 1
	v_mfma_f32_16x16x32_bf16 v[94:97], v[156:159], v[236:239], v[94:97]
	v_mfma_f32_16x16x32_bf16 v[94:97], v[160:163], v[240:243], v[94:97]
	v_mfma_f32_16x16x32_bf16 v[90:93], v[196:199], v[236:239], v[90:93]
	v_mfma_f32_16x16x32_bf16 v[90:93], v[200:203], v[240:243], v[90:93]
	v_mfma_f32_16x16x32_bf16 v[86:89], v[204:207], v[236:239], v[86:89]
	v_mfma_f32_16x16x32_bf16 v[86:89], v[208:211], v[240:243], v[86:89]
	v_mfma_f32_16x16x32_bf16 v[82:85], v[212:215], v[236:239], v[82:85]
	v_mfma_f32_16x16x32_bf16 v[82:85], v[216:219], v[240:243], v[82:85]
	v_mfma_f32_16x16x32_bf16 v[78:81], v[156:159], v[244:247], v[78:81]
	v_mfma_f32_16x16x32_bf16 v[78:81], v[160:163], v[248:251], v[78:81]
	v_mfma_f32_16x16x32_bf16 v[74:77], v[196:199], v[244:247], v[74:77]
	v_mfma_f32_16x16x32_bf16 v[74:77], v[200:203], v[248:251], v[74:77]
	v_mfma_f32_16x16x32_bf16 v[70:73], v[204:207], v[244:247], v[70:73]
	v_mfma_f32_16x16x32_bf16 v[70:73], v[208:211], v[248:251], v[70:73]
	v_mfma_f32_16x16x32_bf16 v[66:69], v[212:215], v[244:247], v[66:69]
	v_mfma_f32_16x16x32_bf16 v[66:69], v[216:219], v[248:251], v[66:69]
	s_setprio 0
	s_barrier
	s_add_i32 s62, s67, s29
	v_lshl_add_u64 v[164:165], s[44:45], 0, v[132:133]
	s_mov_b32 m0, s62
	ds_read_b128 v[220:223], v186 offset:16384
	ds_read_b128 v[224:227], v186 offset:17408
	ds_read_b128 v[228:231], v186 offset:18432
	ds_read_b128 v[232:235], v186 offset:19456
	ds_read_b128 v[236:239], v186 offset:20480
	ds_read_b128 v[240:243], v186 offset:21504
	ds_read_b128 v[244:247], v186 offset:22528
	ds_read_b128 v[248:251], v186 offset:23552
	global_load_lds_dwordx4 v[164:165], off
	s_add_i32 m0, s62, 0x2000
	s_add_u32 s62, s44, 0x4000
	v_lshl_add_u64 v[164:165], s[44:45], 0, v[136:137]
	s_addc_u32 s63, s45, 0
	s_add_i32 s72, s68, s29
	global_load_lds_dwordx4 v[164:165], off
	v_lshl_add_u64 v[164:165], s[62:63], 0, v[132:133]
	s_mov_b32 m0, s72
	s_nop 0
	global_load_lds_dwordx4 v[164:165], off
	v_lshl_add_u64 v[164:165], s[62:63], 0, v[136:137]
	s_add_i32 m0, s72, 0x2000
	s_nop 0
	global_load_lds_dwordx4 v[164:165], off
	s_waitcnt vmcnt(6)
	s_waitcnt lgkmcnt(0)
	s_barrier
; #define PG8_STAGE(bufoff, gbase, voff) do { _Pragma("unroll") for (int _i = 0; _i < 2; ++_i) \
;         __builtin_amdgcn_global_load_lds((const unsigned*)((const char*)(gbase) + (voff)[_i]), (PG8_LAS unsigned*)(lds + (bufoff) + ldsw + _i * 8192), 16, 0, 0); } while (0)
; #define PG8_LDA(dst, b, h) do { _Pragma("unroll") for (int m = 0; m < 4; ++m) _Pragma("unroll") for (int k = 0; k < 2; ++k) dst[m][k] = *(const PG8_LAS bf16x8*)(lds + PG8_SA(b, h) + aoff + m * 2048 + k * 1024); } while (0)
; #define PG8_LDB(dst, b, h) do { _Pragma("unroll") for (int n = 0; n < 2; ++n) _Pragma("unroll") for (int k = 0; k < 2; ++k) dst[n][k] = *(const PG8_LAS bf16x8*)(lds + PG8_SB(b, h) + boff + n * 2048 + k * 1024); } while (0)
; #define PG8_MMA(ai, bj, At, Bt) do { __builtin_amdgcn_s_setprio(1); _Pragma("unroll") for (int m = 0; m < 4; ++m) _Pragma("unroll") for (int n = 0; n < 2; ++n) _Pragma("unroll") for (int k = 0; k < 2; ++k) \
;         acc[ai][bj][m][n] = __builtin_amdgcn_mfma_f32_16x16x32_bf16(Bt[n][k], At[m][k], acc[ai][bj][m][n], 0, 0, 0); __builtin_amdgcn_s_setprio(0); } while (0)
; #define PG8_WAIT_V(n) asm volatile("s_waitcnt vmcnt(" #n ")" ::: "memory")
; #define PG8_WAIT_L(n) asm volatile("s_waitcnt lgkmcnt(" #n ")" ::: "memory")
; #define PG8_BAR __builtin_amdgcn_s_barrier()
; #define PG8_SCHED __builtin_amdgcn_sched_barrier(0)
; template <class Epi, class Sched, bool ALIGN_EPI = false, bool SP2 = false>
; __device__ __forceinline__ void gemm_phase(PG8_LAS unsigned char* lds, const Gemm g, const Sched& S, const Epi& E) {
;     ...
;             PG8_WAIT_V(8); PG8_WAIT_L(0); PG8_BAR; PG8_MMA(1, 0, At, B0); PG8_MMA(1, 1, At, B1); PG8_BAR; PG8_SCHED;
;             PG8_LDB(B0, 1, 0); PG8_LDB(B1, 1, 1); PG8_SCHED; PG8_LDA(At, 1, 0); PG8_STAGE(PG8_SA(0, 1), a2 + hstep, voffA);
;             PG8_WAIT_V(8); PG8_WAIT_L(0); PG8_BAR; PG8_MMA(0, 0, At, B0); PG8_MMA(0, 1, At, B1); PG8_BAR; PG8_SCHED;
	s_setprio 1
	s_waitcnt lgkmcnt(0)
	v_mfma_f32_16x16x32_bf16 v[62:65], v[156:159], v[220:223], v[62:65]
	v_mfma_f32_16x16x32_bf16 v[62:65], v[160:163], v[224:227], v[62:65]
	v_mfma_f32_16x16x32_bf16 v[58:61], v[196:199], v[220:223], v[58:61]
	v_mfma_f32_16x16x32_bf16 v[58:61], v[200:203], v[224:227], v[58:61]
	v_mfma_f32_16x16x32_bf16 v[54:57], v[204:207], v[220:223], v[54:57]
	v_mfma_f32_16x16x32_bf16 v[54:57], v[208:211], v[224:227], v[54:57]
	v_mfma_f32_16x16x32_bf16 v[50:53], v[212:215], v[220:223], v[50:53]
	v_mfma_f32_16x16x32_bf16 v[50:53], v[216:219], v[224:227], v[50:53]
	v_mfma_f32_16x16x32_bf16 v[46:49], v[156:159], v[228:231], v[46:49]
	v_mfma_f32_16x16x32_bf16 v[46:49], v[160:163], v[232:235], v[46:49]
	v_mfma_f32_16x16x32_bf16 v[42:45], v[196:199], v[228:231], v[42:45]
	v_mfma_f32_16x16x32_bf16 v[42:45], v[200:203], v[232:235], v[42:45]
	v_mfma_f32_16x16x32_bf16 v[38:41], v[204:207], v[228:231], v[38:41]
	v_mfma_f32_16x16x32_bf16 v[38:41], v[208:211], v[232:235], v[38:41]
	v_mfma_f32_16x16x32_bf16 v[34:37], v[212:215], v[228:231], v[34:37]
	v_mfma_f32_16x16x32_bf16 v[34:37], v[216:219], v[232:235], v[34:37]
	s_setprio 0
	s_setprio 1
	v_mfma_f32_16x16x32_bf16 v[30:33], v[156:159], v[236:239], v[30:33]
	v_mfma_f32_16x16x32_bf16 v[30:33], v[160:163], v[240:243], v[30:33]
	v_mfma_f32_16x16x32_bf16 v[26:29], v[196:199], v[236:239], v[26:29]
	v_mfma_f32_16x16x32_bf16 v[26:29], v[200:203], v[240:243], v[26:29]
	v_mfma_f32_16x16x32_bf16 v[22:25], v[204:207], v[236:239], v[22:25]
	v_mfma_f32_16x16x32_bf16 v[22:25], v[208:211], v[240:243], v[22:25]
	v_mfma_f32_16x16x32_bf16 v[18:21], v[212:215], v[236:239], v[18:21]
	v_mfma_f32_16x16x32_bf16 v[18:21], v[216:219], v[240:243], v[18:21]
	v_mfma_f32_16x16x32_bf16 v[14:17], v[156:159], v[244:247], v[14:17]
	v_mfma_f32_16x16x32_bf16 v[14:17], v[160:163], v[248:251], v[14:17]
	v_mfma_f32_16x16x32_bf16 v[10:13], v[196:199], v[244:247], v[10:13]
	v_mfma_f32_16x16x32_bf16 v[10:13], v[200:203], v[248:251], v[10:13]
	v_mfma_f32_16x16x32_bf16 v[6:9], v[204:207], v[244:247], v[6:9]
	v_mfma_f32_16x16x32_bf16 v[6:9], v[208:211], v[248:251], v[6:9]
	v_mfma_f32_16x16x32_bf16 v[2:5], v[212:215], v[244:247], v[2:5]
	v_mfma_f32_16x16x32_bf16 v[2:5], v[216:219], v[248:251], v[2:5]
	s_setprio 0
	s_barrier
	s_add_i32 s62, 0, 0x18000
	v_add_u32_e32 v145, s62, v166
	s_add_i32 s63, 0, 0x1c000
	ds_read_b128 v[156:159], v145
	ds_read_b128 v[160:163], v145 offset:1024
	ds_read_b128 v[196:199], v145 offset:2048
	ds_read_b128 v[200:203], v145 offset:3072
	v_add_u32_e32 v145, s63, v166
	ds_read_b128 v[204:207], v145
	ds_read_b128 v[208:211], v145 offset:1024
	ds_read_b128 v[212:215], v145 offset:2048
	ds_read_b128 v[216:219], v145 offset:3072
	v_lshl_add_u64 v[164:165], s[46:47], 0, v[130:131]
	s_mov_b32 m0, s30
	s_nop 0
	global_load_lds_dwordx4 v[164:165], off
	v_lshl_add_u64 v[164:165], s[46:47], 0, v[134:135]
	s_mov_b32 m0, s31
	s_nop 0
	global_load_lds_dwordx4 v[164:165], off
	s_add_u32 s46, s46, 0x4000
	s_addc_u32 s47, s47, 0
	s_mov_b32 m0, s35
	v_lshl_add_u64 v[164:165], s[46:47], 0, v[130:131]
	ds_read_b128 v[220:223], v186 offset:32768
	ds_read_b128 v[224:227], v186 offset:33792
	ds_read_b128 v[228:231], v186 offset:34816
	ds_read_b128 v[232:235], v186 offset:35840
	ds_read_b128 v[236:239], v186 offset:36864
	ds_read_b128 v[240:243], v186 offset:37888
	ds_read_b128 v[244:247], v186 offset:38912
	ds_read_b128 v[248:251], v186 offset:39936
	global_load_lds_dwordx4 v[164:165], off
	v_lshl_add_u64 v[164:165], s[46:47], 0, v[134:135]
	s_mov_b32 m0, s48
	s_nop 0
	global_load_lds_dwordx4 v[164:165], off
	s_waitcnt vmcnt(8)
	s_waitcnt lgkmcnt(0)
	s_barrier
; #define PG8_STAGE(bufoff, gbase, voff) do { _Pragma("unroll") for (int _i = 0; _i < 2; ++_i) \
;         __builtin_amdgcn_global_load_lds((const unsigned*)((const char*)(gbase) + (voff)[_i]), (PG8_LAS unsigned*)(lds + (bufoff) + ldsw + _i * 8192), 16, 0, 0); } while (0)
; #define PG8_LDA(dst, b, h) do { _Pragma("unroll") for (int m = 0; m < 4; ++m) _Pragma("unroll") for (int k = 0; k < 2; ++k) dst[m][k] = *(const PG8_LAS bf16x8*)(lds + PG8_SA(b, h) + aoff + m * 2048 + k * 1024); } while (0)
; #define PG8_MMA(ai, bj, At, Bt) do { __builtin_amdgcn_s_setprio(1); _Pragma("unroll") for (int m = 0; m < 4; ++m) _Pragma("unroll") for (int n = 0; n < 2; ++n) _Pragma("unroll") for (int k = 0; k < 2; ++k) \
;         acc[ai][bj][m][n] = __builtin_amdgcn_mfma_f32_16x16x32_bf16(Bt[n][k], At[m][k], acc[ai][bj][m][n], 0, 0, 0); __builtin_amdgcn_s_setprio(0); } while (0)
; #define PG8_WAIT_V(n) asm volatile("s_waitcnt vmcnt(" #n ")" ::: "memory")
; #define PG8_WAIT_L(n) asm volatile("s_waitcnt lgkmcnt(" #n ")" ::: "memory")
; #define PG8_BAR __builtin_amdgcn_s_barrier()
; #define PG8_SCHED __builtin_amdgcn_sched_barrier(0)
; template <class Epi, class Sched, bool ALIGN_EPI = false, bool SP2 = false>
; __device__ __forceinline__ void gemm_phase(PG8_LAS unsigned char* lds, const Gemm g, const Sched& S, const Epi& E) {
;     ...
;             PG8_WAIT_V(8); PG8_WAIT_L(0); PG8_BAR; PG8_MMA(0, 0, At, B0); PG8_MMA(0, 1, At, B1); PG8_BAR; PG8_SCHED;
;             PG8_LDA(At, 1, 1); PG8_STAGE(PG8_SB(1, 0), b3, voffB); PG8_STAGE(PG8_SB(1, 1), b3 + hstep, voffB); PG8_STAGE(PG8_SA(1, 0), a3, voffA);
;             PG8_WAIT_V(8); PG8_WAIT_L(0); PG8_BAR; PG8_MMA(1, 0, At, B0); PG8_MMA(1, 1, At, B1); PG8_BAR; PG8_SCHED;
	s_setprio 1
	s_waitcnt lgkmcnt(0)
	v_mfma_f32_16x16x32_bf16 v[126:129], v[156:159], v[220:223], v[126:129]
	v_mfma_f32_16x16x32_bf16 v[126:129], v[160:163], v[224:227], v[126:129]
	v_mfma_f32_16x16x32_bf16 v[122:125], v[196:199], v[220:223], v[122:125]
	v_mfma_f32_16x16x32_bf16 v[122:125], v[200:203], v[224:227], v[122:125]
	v_mfma_f32_16x16x32_bf16 v[118:121], v[204:207], v[220:223], v[118:121]
	v_mfma_f32_16x16x32_bf16 v[118:121], v[208:211], v[224:227], v[118:121]
	v_mfma_f32_16x16x32_bf16 v[114:117], v[212:215], v[220:223], v[114:117]
	v_mfma_f32_16x16x32_bf16 v[114:117], v[216:219], v[224:227], v[114:117]
	v_mfma_f32_16x16x32_bf16 v[110:113], v[156:159], v[228:231], v[110:113]
	v_mfma_f32_16x16x32_bf16 v[110:113], v[160:163], v[232:235], v[110:113]
	v_mfma_f32_16x16x32_bf16 v[106:109], v[196:199], v[228:231], v[106:109]
	v_mfma_f32_16x16x32_bf16 v[106:109], v[200:203], v[232:235], v[106:109]
	v_mfma_f32_16x16x32_bf16 v[102:105], v[204:207], v[228:231], v[102:105]
	v_mfma_f32_16x16x32_bf16 v[102:105], v[208:211], v[232:235], v[102:105]
	v_mfma_f32_16x16x32_bf16 v[98:101], v[212:215], v[228:231], v[98:101]
	v_mfma_f32_16x16x32_bf16 v[98:101], v[216:219], v[232:235], v[98:101]
	s_setprio 0
	s_setprio 1
	v_mfma_f32_16x16x32_bf16 v[94:97], v[156:159], v[236:239], v[94:97]
	v_mfma_f32_16x16x32_bf16 v[94:97], v[160:163], v[240:243], v[94:97]
	v_mfma_f32_16x16x32_bf16 v[90:93], v[196:199], v[236:239], v[90:93]
	v_mfma_f32_16x16x32_bf16 v[90:93], v[200:203], v[240:243], v[90:93]
	v_mfma_f32_16x16x32_bf16 v[86:89], v[204:207], v[236:239], v[86:89]
	v_mfma_f32_16x16x32_bf16 v[86:89], v[208:211], v[240:243], v[86:89]
	v_mfma_f32_16x16x32_bf16 v[82:85], v[212:215], v[236:239], v[82:85]
	v_mfma_f32_16x16x32_bf16 v[82:85], v[216:219], v[240:243], v[82:85]
	v_mfma_f32_16x16x32_bf16 v[78:81], v[156:159], v[244:247], v[78:81]
	v_mfma_f32_16x16x32_bf16 v[78:81], v[160:163], v[248:251], v[78:81]
	v_mfma_f32_16x16x32_bf16 v[74:77], v[196:199], v[244:247], v[74:77]
	v_mfma_f32_16x16x32_bf16 v[74:77], v[200:203], v[248:251], v[74:77]
	v_mfma_f32_16x16x32_bf16 v[70:73], v[204:207], v[244:247], v[70:73]
	v_mfma_f32_16x16x32_bf16 v[70:73], v[208:211], v[248:251], v[70:73]
	v_mfma_f32_16x16x32_bf16 v[66:69], v[212:215], v[244:247], v[66:69]
	v_mfma_f32_16x16x32_bf16 v[66:69], v[216:219], v[248:251], v[66:69]
	s_setprio 0
	s_barrier
	s_add_u32 s46, s44, 0x8000
	s_addc_u32 s47, s45, 0
	s_add_i32 s62, s62, s29
	v_lshl_add_u64 v[164:165], s[46:47], 0, v[132:133]
	s_mov_b32 m0, s62
	ds_read_b128 v[220:223], v186 offset:49152
	ds_read_b128 v[224:227], v186 offset:50176
	ds_read_b128 v[228:231], v186 offset:51200
	ds_read_b128 v[232:235], v186 offset:52224
	ds_read_b128 v[236:239], v186 offset:53248
	ds_read_b128 v[240:243], v186 offset:54272
	ds_read_b128 v[244:247], v186 offset:55296
	ds_read_b128 v[248:251], v186 offset:56320
	global_load_lds_dwordx4 v[164:165], off
	s_add_i32 m0, s62, 0x2000
	s_add_u32 s44, s44, 0xc000
	v_lshl_add_u64 v[164:165], s[46:47], 0, v[136:137]
	s_addc_u32 s45, s45, 0
	s_add_i32 s46, s63, s29
	global_load_lds_dwordx4 v[164:165], off
	v_lshl_add_u64 v[164:165], s[44:45], 0, v[132:133]
	s_mov_b32 m0, s46
	s_nop 0
	global_load_lds_dwordx4 v[164:165], off
	v_lshl_add_u64 v[164:165], s[44:45], 0, v[136:137]
	s_add_i32 m0, s46, 0x2000
	s_nop 0
	global_load_lds_dwordx4 v[164:165], off
	s_waitcnt vmcnt(6)
	s_waitcnt lgkmcnt(0)
	s_barrier
	s_setprio 1
	s_waitcnt lgkmcnt(0)
	v_mfma_f32_16x16x32_bf16 v[62:65], v[156:159], v[220:223], v[62:65]
	v_mfma_f32_16x16x32_bf16 v[62:65], v[160:163], v[224:227], v[62:65]
	v_mfma_f32_16x16x32_bf16 v[58:61], v[196:199], v[220:223], v[58:61]
	v_mfma_f32_16x16x32_bf16 v[58:61], v[200:203], v[224:227], v[58:61]
	v_mfma_f32_16x16x32_bf16 v[54:57], v[204:207], v[220:223], v[54:57]
	v_mfma_f32_16x16x32_bf16 v[54:57], v[208:211], v[224:227], v[54:57]
	v_mfma_f32_16x16x32_bf16 v[50:53], v[212:215], v[220:223], v[50:53]
	v_mfma_f32_16x16x32_bf16 v[50:53], v[216:219], v[224:227], v[50:53]
	v_mfma_f32_16x16x32_bf16 v[46:49], v[156:159], v[228:231], v[46:49]
	v_mfma_f32_16x16x32_bf16 v[46:49], v[160:163], v[232:235], v[46:49]
	v_mfma_f32_16x16x32_bf16 v[42:45], v[196:199], v[228:231], v[42:45]
	v_mfma_f32_16x16x32_bf16 v[42:45], v[200:203], v[232:235], v[42:45]
	v_mfma_f32_16x16x32_bf16 v[38:41], v[204:207], v[228:231], v[38:41]
	v_mfma_f32_16x16x32_bf16 v[38:41], v[208:211], v[232:235], v[38:41]
	v_mfma_f32_16x16x32_bf16 v[34:37], v[212:215], v[228:231], v[34:37]
	v_mfma_f32_16x16x32_bf16 v[34:37], v[216:219], v[232:235], v[34:37]
	s_setprio 0
	s_setprio 1
	v_mfma_f32_16x16x32_bf16 v[30:33], v[156:159], v[236:239], v[30:33]
	v_mfma_f32_16x16x32_bf16 v[30:33], v[160:163], v[240:243], v[30:33]
	v_mfma_f32_16x16x32_bf16 v[26:29], v[196:199], v[236:239], v[26:29]
	v_mfma_f32_16x16x32_bf16 v[26:29], v[200:203], v[240:243], v[26:29]
	v_mfma_f32_16x16x32_bf16 v[22:25], v[204:207], v[236:239], v[22:25]
	v_mfma_f32_16x16x32_bf16 v[22:25], v[208:211], v[240:243], v[22:25]
	v_mfma_f32_16x16x32_bf16 v[18:21], v[212:215], v[236:239], v[18:21]
	v_mfma_f32_16x16x32_bf16 v[18:21], v[216:219], v[240:243], v[18:21]
	v_mfma_f32_16x16x32_bf16 v[14:17], v[156:159], v[244:247], v[14:17]
	v_mfma_f32_16x16x32_bf16 v[14:17], v[160:163], v[248:251], v[14:17]
	v_mfma_f32_16x16x32_bf16 v[10:13], v[196:199], v[244:247], v[10:13]
	v_mfma_f32_16x16x32_bf16 v[10:13], v[200:203], v[248:251], v[10:13]
	v_mfma_f32_16x16x32_bf16 v[6:9], v[204:207], v[244:247], v[6:9]
	v_mfma_f32_16x16x32_bf16 v[6:9], v[208:211], v[248:251], v[6:9]
	v_mfma_f32_16x16x32_bf16 v[2:5], v[212:215], v[244:247], v[2:5]
	v_mfma_f32_16x16x32_bf16 v[2:5], v[216:219], v[248:251], v[2:5]
	s_setprio 0
	s_barrier
	s_cmpk_gt_u32 s59, 0xa9
	s_mov_b32 s59, s24
	s_cbranch_scc0 .LBB0_939
	s_and_b64 vcc, exec, s[38:39]
	s_cbranch_vccz .LBB0_942
	s_barrier
